# v21: v17 plus nt stores for the LN1 bf16 residual stream (not re-read until the combine phase)
# speedup vs baseline: 1.0621x; 1.0019x over previous
.LBB0_458:
	s_waitcnt vmcnt(0) lgkmcnt(0)
	v_lshlrev_b32_e32 v85, 16, v37
	v_lshlrev_b32_e32 v84, 16, v36
	v_and_b32_e32 v37, 0xffff0000, v37
	v_and_b32_e32 v36, 0xffff0000, v36
	v_pk_add_f32 v[68:69], v[84:85], v[36:37]
	v_lshlrev_b32_e32 v87, 16, v35
	v_lshlrev_b32_e32 v86, 16, v34
	v_and_b32_e32 v35, 0xffff0000, v35
	v_and_b32_e32 v34, 0xffff0000, v34
	v_lshlrev_b32_e32 v46, 16, v39
	v_and_b32_e32 v48, 0xffff0000, v39
	v_add_f32_e32 v39, v68, v69
	v_pk_add_f32 v[68:69], v[86:87], v[34:35]
	v_lshlrev_b32_e32 v42, 16, v40
	v_and_b32_e32 v43, 0xffff0000, v40
	v_lshlrev_b32_e32 v40, 16, v41
	v_and_b32_e32 v41, 0xffff0000, v41
	v_pk_add_f32 v[68:69], v[68:69], v[68:69] op_sel_hi:[0,1]
	v_lshlrev_b32_e32 v44, 16, v38
	v_and_b32_e32 v38, 0xffff0000, v38
	v_add_f32_e32 v49, 0, v39
	v_add_f32_e32 v45, v42, v43
	v_add_f32_e32 v39, v40, v41
	v_mov_b32_e32 v47, v69
	v_pk_add_f32 v[70:71], v[44:45], v[38:39]
	v_pk_add_f32 v[68:69], v[46:47], v[48:49]
	s_min_u32 s0, s36, 29
	v_pk_add_f32 v[68:69], v[70:71], v[68:69]
	s_lshl_b32 s0, s0, 3
	v_add_f32_e32 v39, v68, v69
	s_add_i32 s18, s35, s0
	s_nop 0
	v_add_f32_dpp v39, v39, v39 quad_perm:[1,0,3,2] row_mask:0xf bank_mask:0xf bound_ctrl:1
	s_nop 1
	v_add_f32_dpp v39, v39, v39 quad_perm:[2,3,0,1] row_mask:0xf bank_mask:0xf bound_ctrl:1
	s_nop 1
	v_add_f32_dpp v39, v39, v39 row_half_mirror row_mask:0xf bank_mask:0xf bound_ctrl:1
	s_nop 1
	v_add_f32_dpp v39, v39, v39 row_mirror row_mask:0xf bank_mask:0xf bound_ctrl:1
	s_nop 0
	v_readlane_b32 s19, v39, 16
	v_readlane_b32 s20, v39, 48
	v_readlane_b32 s0, v39, 0
	v_readlane_b32 s1, v39, 32
	v_mov_b32_e32 v68, s19
	v_mov_b32_e32 v69, s20
	v_pk_add_f32 v[68:69], s[0:1], v[68:69]
	s_nop 0
	v_add_f32_e32 v39, v68, v69
	v_fmac_f32_e32 v36, 0xba800000, v39
	v_fmac_f32_e32 v37, 0xba800000, v39
	v_fmac_f32_e32 v85, 0xba800000, v39
	v_fmac_f32_e32 v84, 0xba800000, v39
	v_mov_b32_e32 v88, v85
	v_mov_b32_e32 v89, v37
	v_mov_b32_e32 v85, v36
	v_fmac_f32_e32 v34, 0xba800000, v39
	v_fmac_f32_e32 v35, 0xba800000, v39
	v_fmac_f32_e32 v87, 0xba800000, v39
	v_pk_mul_f32 v[68:69], v[88:89], v[88:89]
	v_pk_mul_f32 v[36:37], v[84:85], v[84:85]
	v_fmac_f32_e32 v86, 0xba800000, v39
	v_mov_b32_e32 v90, v87
	v_mov_b32_e32 v91, v35
	v_mov_b32_e32 v87, v34
	v_pk_mov_b32 v[70:71], v[36:37], v[68:69] op_sel:[1,0]
	v_mov_b32_e32 v37, v69
	v_pk_mul_f32 v[68:69], v[90:91], v[90:91]
	v_pk_mul_f32 v[34:35], v[86:87], v[86:87]
	v_pk_add_f32 v[36:37], v[70:71], v[36:37]
	v_pk_mov_b32 v[70:71], v[34:35], v[68:69] op_sel:[1,0]
	v_mov_b32_e32 v35, v69
	v_pk_add_f32 v[34:35], v[70:71], v[34:35]
	v_fmac_f32_e32 v42, 0xba800000, v39
	v_pk_add_f32 v[34:35], v[34:35], v[34:35] op_sel_hi:[0,1]
	v_fmac_f32_e32 v43, 0xba800000, v39
	v_fmac_f32_e32 v40, 0xba800000, v39
	v_mul_f32_e32 v34, v42, v42
	v_fmac_f32_e32 v41, 0xba800000, v39
	v_pk_fma_f32 v[68:69], v[42:43], v[42:43], v[34:35] op_sel_hi:[1,1,0]
	v_mul_f32_e32 v34, v40, v40
	v_pk_add_f32 v[36:37], v[36:37], v[36:37] op_sel_hi:[0,1]
	v_pk_fma_f32 v[70:71], v[40:41], v[40:41], v[34:35] op_sel_hi:[1,1,0]
	v_fmac_f32_e32 v48, 0xba800000, v39
	v_fmac_f32_e32 v46, 0xba800000, v39
	v_fmac_f32_e32 v38, 0xba800000, v39
	v_fmac_f32_e32 v44, 0xba800000, v39
	v_mul_f32_e32 v68, v44, v44
	v_mul_f32_e32 v70, v38, v38
	v_mul_f32_e32 v36, v46, v46
	v_mul_f32_e32 v34, v48, v48
	v_pk_add_f32 v[68:69], v[68:69], v[70:71]
	v_pk_add_f32 v[34:35], v[36:37], v[34:35]
	v_mov_b32_e32 v47, v48
	v_pk_add_f32 v[34:35], v[68:69], v[34:35]
	s_nop 0
	v_add_f32_e32 v34, v34, v35
	s_nop 1
	v_add_f32_dpp v34, v34, v34 quad_perm:[1,0,3,2] row_mask:0xf bank_mask:0xf bound_ctrl:1
	s_nop 1
	v_add_f32_dpp v34, v34, v34 quad_perm:[2,3,0,1] row_mask:0xf bank_mask:0xf bound_ctrl:1
	s_nop 1
	v_add_f32_dpp v34, v34, v34 row_half_mirror row_mask:0xf bank_mask:0xf bound_ctrl:1
	s_nop 1
	v_add_f32_dpp v34, v34, v34 row_mirror row_mask:0xf bank_mask:0xf bound_ctrl:1
	s_nop 0
	v_readlane_b32 s19, v34, 16
	v_readlane_b32 s20, v34, 48
	v_readlane_b32 s0, v34, 0
	v_readlane_b32 s1, v34, 32
	v_mov_b32_e32 v34, s19
	v_mov_b32_e32 v35, s20
	v_pk_add_f32 v[34:35], s[0:1], v[34:35]
	s_ashr_i32 s19, s18, 31
	v_add_f32_e32 v34, v34, v35
	v_fmamk_f32 v34, v34, 0x3a800000, v80
	v_mul_f32_e32 v35, 0x4f800000, v34
	v_cmp_gt_f32_e32 vcc, s7, v34
	s_lshl_b64 s[0:1], s[18:19], 11
	s_and_b32 s20, s36, 3
	v_cndmask_b32_e32 v36, v34, v35, vcc
	v_lshl_add_u64 v[34:35], v[54:55], 0, s[0:1]
	global_load_dwordx2 v[68:69], v[34:35], off
	global_load_dwordx2 v[70:71], v[34:35], off offset:512
	global_load_dwordx2 v[72:73], v[34:35], off offset:1024
	global_load_dwordx2 v[74:75], v[34:35], off offset:1536
	v_sqrt_f32_e32 v37, v36
	s_mul_i32 s30, s20, 0x810
	s_add_i32 s30, s87, s30
	v_add_u32_e32 v39, -1, v37
	v_fma_f32 v45, -v39, v37, v36
	v_cmp_ge_f32_e64 s[18:19], 0, v45
	v_add_u32_e32 v45, 1, v37
	s_nop 0
	v_cndmask_b32_e64 v39, v37, v39, s[18:19]
	v_fma_f32 v37, -v45, v37, v36
	v_cmp_lt_f32_e64 s[18:19], 0, v37
	s_nop 1
	v_cndmask_b32_e64 v37, v39, v45, s[18:19]
	v_mul_f32_e32 v39, 0x37800000, v37
	v_cndmask_b32_e32 v37, v37, v39, vcc
	v_cmp_class_f32_e32 vcc, v36, v81
	s_add_i32 s18, s4, s34
	s_ashr_i32 s19, s18, 31
	v_cndmask_b32_e32 v36, v37, v36, vcc
	v_div_scale_f32 v37, s[0:1], v36, v36, 1.0
	v_rcp_f32_e32 v39, v37
	s_lshl_b64 s[0:1], s[18:19], 11
	v_fma_f32 v34, -v37, v39, 1.0
	v_fmac_f32_e32 v39, v34, v39
	v_div_scale_f32 v34, vcc, 1.0, v36, 1.0
	v_mul_f32_e32 v35, v34, v39
	v_fma_f32 v45, -v37, v35, v34
	v_fmac_f32_e32 v35, v45, v39
	v_fma_f32 v34, -v37, v35, v34
	v_div_fmas_f32 v34, v34, v39, v35
	v_div_fixup_f32 v34, v34, v36, 1.0
	v_mov_b32_e32 v45, v38
	v_pk_mul_f32 v[36:37], v[84:85], v[34:35] op_sel_hi:[1,0]
	v_pk_mul_f32 v[84:85], v[88:89], v[34:35] op_sel_hi:[1,0]
	v_pk_mul_f32 v[38:39], v[44:45], v[34:35] op_sel_hi:[1,0]
	v_mov_b32_e32 v44, v150
	v_pk_fma_f32 v[84:85], v[4:5], v[84:85], v[12:13]
	v_pk_fma_f32 v[36:37], v[2:3], v[36:37], v[10:11]
	v_pk_mul_f32 v[86:87], v[86:87], v[34:35] op_sel_hi:[1,0]
	v_pk_mul_f32 v[88:89], v[90:91], v[34:35] op_sel_hi:[1,0]
	v_pk_fma_f32 v[86:87], v[6:7], v[86:87], v[14:15]
	v_pk_fma_f32 v[88:89], v[8:9], v[88:89], v[16:17]
	v_pk_mul_f32 v[42:43], v[42:43], v[34:35] op_sel_hi:[1,0]
	v_pk_mul_f32 v[40:41], v[40:41], v[34:35] op_sel_hi:[1,0]
	v_pk_mul_f32 v[34:35], v[46:47], v[34:35] op_sel_hi:[1,0]
	v_lshl_add_u32 v48, v44, 3, s30
	v_cvt_pk_bf16_f32 v44, v36, v37
	v_cvt_pk_bf16_f32 v45, v84, v85
	v_lshl_add_u64 v[46:47], v[56:57], 0, s[0:1]
	v_pk_fma_f32 v[40:41], v[20:21], v[40:41], v[28:29]
	v_pk_fma_f32 v[42:43], v[18:19], v[42:43], v[26:27]
	global_store_dwordx2 v[46:47], v[44:45], off nt
	ds_write_b64 v48, v[44:45] offset:33024
	v_cvt_pk_bf16_f32 v44, v86, v87
	v_cvt_pk_bf16_f32 v45, v88, v89
	v_pk_fma_f32 v[34:35], v[24:25], v[34:35], v[32:33]
	v_pk_fma_f32 v[38:39], v[22:23], v[38:39], v[30:31]
	global_store_dwordx2 v[46:47], v[44:45], off offset:512 nt
	ds_write_b64 v48, v[44:45] offset:33536
	v_cvt_pk_bf16_f32 v44, v42, v43
	v_cvt_pk_bf16_f32 v45, v40, v41
	global_store_dwordx2 v[46:47], v[44:45], off offset:1024 nt
	ds_write_b64 v48, v[44:45] offset:34048
	v_cvt_pk_bf16_f32 v44, v38, v39
	v_cvt_pk_bf16_f32 v45, v34, v35
	global_store_dwordx2 v[46:47], v[44:45], off offset:1536 nt
	ds_write_b64 v48, v[44:45] offset:34560
	v_med3_f32 v36, v36, s38, v82
	v_med3_f32 v37, v37, s38, v82
	v_mov_b32_e32 v44, 0
	v_cvt_pk_fp8_f32 v44, v36, v37
	v_med3_f32 v36, v84, s38, v82
	v_med3_f32 v37, v85, s38, v82
	v_med3_f32 v45, v86, s38, v82
	v_cvt_pk_fp8_f32 v44, v36, v37 op_sel:[0,0,1]
	v_med3_f32 v46, v87, s38, v82
	v_mov_b32_e32 v47, 0
	v_cvt_pk_fp8_f32 v47, v45, v46
	s_lshl_b64 s[0:1], s[18:19], 10
	v_lshl_add_u64 v[36:37], v[58:59], 0, s[0:1]
	global_store_dword v[36:37], v44, off
	v_med3_f32 v44, v88, s38, v82
	v_med3_f32 v45, v89, s38, v82
	v_cvt_pk_fp8_f32 v47, v44, v45 op_sel:[0,0,1]
	v_med3_f32 v42, v42, s38, v82
	v_med3_f32 v43, v43, s38, v82
	v_mov_b32_e32 v44, 0
	v_cvt_pk_fp8_f32 v44, v42, v43
	v_med3_f32 v38, v38, s38, v82
	v_med3_f32 v39, v39, s38, v82
	v_mov_b32_e32 v42, 0
	v_cvt_pk_fp8_f32 v42, v38, v39
	v_med3_f32 v34, v34, s38, v82
	v_med3_f32 v35, v35, s38, v82
	v_med3_f32 v40, v40, s38, v82
	v_med3_f32 v41, v41, s38, v82
	v_cvt_pk_fp8_f32 v42, v34, v35 op_sel:[0,0,1]
	v_cvt_pk_fp8_f32 v44, v40, v41 op_sel:[0,0,1]
	s_cmp_lg_u32 s20, 3
	global_store_dword v[36:37], v47, off offset:256
	global_store_dword v[36:37], v44, off offset:512
	global_store_dword v[36:37], v42, off offset:768
	s_cbranch_scc1 .LBB0_457
	v_mov_b32_e32 v100, v150
	s_nop 0
	v_and_b32_e32 v34, 3, v100
	v_mul_u32_u24_e32 v34, 0x810, v34
	v_and_b32_e32 v38, -16, v100
	v_add3_u32 v83, s87, v34, v38
	ds_read_b128 v[34:37], v83 offset:33024
	v_and_b32_e32 v39, 15, v100
	v_mul_u32_u24_e32 v39, 0x810, v39
	v_add3_u32 v101, 0, v39, v38
	ds_read_b128 v[38:41], v83 offset:33088
	ds_read_b128 v[42:45], v101
	ds_read_b128 v[46:49], v101 offset:64
	s_waitcnt lgkmcnt(0)
	v_mfma_f32_16x16x32_bf16 v[38:41], v[38:41], v[46:49], 0
	v_cmp_gt_i32_e32 vcc, 16, v100
	v_mfma_f32_16x16x32_bf16 v[34:37], v[34:37], v[42:45], 0
	ds_read_b128 v[42:45], v83 offset:33152
	ds_read_b128 v[46:49], v83 offset:33216
	ds_read_b128 v[84:87], v101 offset:128
	ds_read_b128 v[88:91], v101 offset:192
	s_waitcnt lgkmcnt(0)
	v_mfma_f32_16x16x32_bf16 v[42:45], v[42:45], v[84:87], 0
	ds_read_b128 v[84:87], v83 offset:33280
	v_mfma_f32_16x16x32_bf16 v[46:49], v[46:49], v[88:91], 0
	ds_read_b128 v[88:91], v83 offset:33344
	ds_read_b128 v[92:95], v101 offset:256
	ds_read_b128 v[96:99], v101 offset:320
	s_waitcnt lgkmcnt(0)
	v_mfma_f32_16x16x32_bf16 v[34:37], v[84:87], v[92:95], v[34:37]
	ds_read_b128 v[84:87], v83 offset:33408
	v_mfma_f32_16x16x32_bf16 v[38:41], v[88:91], v[96:99], v[38:41]
	ds_read_b128 v[88:91], v83 offset:33472
	ds_read_b128 v[92:95], v101 offset:384
	ds_read_b128 v[96:99], v101 offset:448
	s_waitcnt lgkmcnt(0)
	v_mfma_f32_16x16x32_bf16 v[42:45], v[84:87], v[92:95], v[42:45]
	ds_read_b128 v[84:87], v83 offset:33536
	v_mfma_f32_16x16x32_bf16 v[46:49], v[88:91], v[96:99], v[46:49]
	ds_read_b128 v[88:91], v83 offset:33600
	ds_read_b128 v[92:95], v101 offset:512
	ds_read_b128 v[96:99], v101 offset:576
	s_waitcnt lgkmcnt(0)
	v_mfma_f32_16x16x32_bf16 v[34:37], v[84:87], v[92:95], v[34:37]
	ds_read_b128 v[84:87], v83 offset:33664
	v_mfma_f32_16x16x32_bf16 v[38:41], v[88:91], v[96:99], v[38:41]
	ds_read_b128 v[88:91], v83 offset:33728
	ds_read_b128 v[92:95], v101 offset:640
	ds_read_b128 v[96:99], v101 offset:704
	s_waitcnt lgkmcnt(0)
	v_mfma_f32_16x16x32_bf16 v[42:45], v[84:87], v[92:95], v[42:45]
	ds_read_b128 v[84:87], v83 offset:33792
	ds_read_b128 v[92:95], v83 offset:33856
	v_mfma_f32_16x16x32_bf16 v[46:49], v[88:91], v[96:99], v[46:49]
	ds_read_b128 v[88:91], v101 offset:768
	ds_read_b128 v[96:99], v101 offset:832
	s_waitcnt lgkmcnt(0)
	v_mfma_f32_16x16x32_bf16 v[34:37], v[84:87], v[88:91], v[34:37]
	ds_read_b128 v[84:87], v83 offset:33920
	ds_read_b128 v[88:91], v83 offset:33984
	v_mfma_f32_16x16x32_bf16 v[38:41], v[92:95], v[96:99], v[38:41]
	ds_read_b128 v[92:95], v101 offset:896
	ds_read_b128 v[96:99], v101 offset:960
	s_waitcnt lgkmcnt(0)
	v_mfma_f32_16x16x32_bf16 v[42:45], v[84:87], v[92:95], v[42:45]
	ds_read_b128 v[84:87], v83 offset:34048
	ds_read_b128 v[92:95], v83 offset:34112
	v_mfma_f32_16x16x32_bf16 v[46:49], v[88:91], v[96:99], v[46:49]
	ds_read_b128 v[88:91], v101 offset:1024
	ds_read_b128 v[96:99], v101 offset:1088
	s_waitcnt lgkmcnt(0)
	v_mfma_f32_16x16x32_bf16 v[34:37], v[84:87], v[88:91], v[34:37]
	ds_read_b128 v[84:87], v83 offset:34176
	ds_read_b128 v[88:91], v83 offset:34240
	v_mfma_f32_16x16x32_bf16 v[38:41], v[92:95], v[96:99], v[38:41]
	ds_read_b128 v[92:95], v101 offset:1152
	ds_read_b128 v[96:99], v101 offset:1216
	s_waitcnt lgkmcnt(0)
	v_mfma_f32_16x16x32_bf16 v[42:45], v[84:87], v[92:95], v[42:45]
	ds_read_b128 v[84:87], v83 offset:34304
	ds_read_b128 v[92:95], v83 offset:34368
	v_mfma_f32_16x16x32_bf16 v[46:49], v[88:91], v[96:99], v[46:49]
	ds_read_b128 v[88:91], v101 offset:1280
	ds_read_b128 v[96:99], v101 offset:1344
	s_waitcnt lgkmcnt(0)
	v_mfma_f32_16x16x32_bf16 v[34:37], v[84:87], v[88:91], v[34:37]
	ds_read_b128 v[84:87], v83 offset:34432
	ds_read_b128 v[88:91], v83 offset:34496
	v_mfma_f32_16x16x32_bf16 v[38:41], v[92:95], v[96:99], v[38:41]
	ds_read_b128 v[92:95], v101 offset:1408
	ds_read_b128 v[96:99], v101 offset:1472
	s_waitcnt lgkmcnt(0)
	v_mfma_f32_16x16x32_bf16 v[42:45], v[84:87], v[92:95], v[42:45]
	ds_read_b128 v[84:87], v83 offset:34560
	ds_read_b128 v[92:95], v83 offset:34624
	v_mfma_f32_16x16x32_bf16 v[46:49], v[88:91], v[96:99], v[46:49]
	ds_read_b128 v[88:91], v101 offset:1536
	ds_read_b128 v[96:99], v101 offset:1600
	s_waitcnt lgkmcnt(0)
	v_mfma_f32_16x16x32_bf16 v[34:37], v[84:87], v[88:91], v[34:37]
	ds_read_b128 v[84:87], v83 offset:34688
	ds_read_b128 v[88:91], v83 offset:34752
	v_mfma_f32_16x16x32_bf16 v[38:41], v[92:95], v[96:99], v[38:41]
	ds_read_b128 v[92:95], v101 offset:1664
	ds_read_b128 v[96:99], v101 offset:1728
	s_waitcnt lgkmcnt(0)
	v_mfma_f32_16x16x32_bf16 v[42:45], v[84:87], v[92:95], v[42:45]
	ds_read_b128 v[84:87], v83 offset:34816
	ds_read_b128 v[92:95], v83 offset:34880
	v_mfma_f32_16x16x32_bf16 v[46:49], v[88:91], v[96:99], v[46:49]
	ds_read_b128 v[88:91], v101 offset:1792
	ds_read_b128 v[96:99], v101 offset:1856
	s_waitcnt lgkmcnt(0)
	v_mfma_f32_16x16x32_bf16 v[34:37], v[84:87], v[88:91], v[34:37]
	ds_read_b128 v[84:87], v83 offset:34944
	ds_read_b128 v[88:91], v83 offset:35008
	v_mfma_f32_16x16x32_bf16 v[38:41], v[92:95], v[96:99], v[38:41]
	ds_read_b128 v[92:95], v101 offset:1920
	ds_read_b128 v[96:99], v101 offset:1984
	v_ashrrev_i32_e32 v101, 31, v100
	s_waitcnt lgkmcnt(0)
	v_mfma_f32_16x16x32_bf16 v[42:45], v[84:87], v[92:95], v[42:45]
	s_nop 2
	v_add_f32_e64 v34, v34, v38
	v_add_f32_e64 v35, v35, v39
	v_mfma_f32_16x16x32_bf16 v[46:49], v[88:91], v[96:99], v[46:49]
	s_nop 7
	v_pk_add_f32 v[38:39], v[42:43], v[46:47]
	s_nop 0
	v_pk_add_f32 v[38:39], v[34:35], v[38:39]
	s_nop 1
	v_mov_b32_dpp v34, v38 quad_perm:[1,0,3,2] row_mask:0xf bank_mask:0xf bound_ctrl:1
	v_max_f32_e32 v34, v34, v34
	v_max_f32_e32 v34, v38, v34
	s_nop 1
	v_mov_b32_dpp v35, v34 quad_perm:[2,3,0,1] row_mask:0xf bank_mask:0xf bound_ctrl:1
	v_max_f32_e32 v35, v35, v35
	v_max_f32_e32 v34, v34, v35
	s_nop 1
	v_mov_b32_dpp v35, v34 row_half_mirror row_mask:0xf bank_mask:0xf bound_ctrl:1
	v_max_f32_e32 v35, v35, v35
	v_max_f32_e32 v34, v34, v35
	s_nop 1
	v_mov_b32_dpp v35, v34 row_mirror row_mask:0xf bank_mask:0xf bound_ctrl:1
	v_max_f32_e32 v35, v35, v35
	v_max_f32_e32 v34, v34, v35
	v_sub_f32_e32 v34, v38, v34
	v_mul_f32_e32 v34, 0x3fb8aa3b, v34
	v_exp_f32_e32 v38, v34
	v_lshlrev_b64 v[34:35], 13, v[100:101]
	v_lshl_add_u64 v[34:35], s[26:27], 0, v[34:35]
	v_add_f32_dpp v42, v38, v38 quad_perm:[1,0,3,2] row_mask:0xf bank_mask:0xf bound_ctrl:1
	s_nop 1
	v_add_f32_dpp v42, v42, v42 quad_perm:[2,3,0,1] row_mask:0xf bank_mask:0xf bound_ctrl:1
	s_nop 1
	v_add_f32_dpp v42, v42, v42 row_half_mirror row_mask:0xf bank_mask:0xf bound_ctrl:1
	s_nop 1
	v_mov_b32_dpp v43, v42 row_mirror row_mask:0xf bank_mask:0xf bound_ctrl:1
	s_and_saveexec_b64 s[30:31], vcc
	s_cbranch_execz .LBB0_461
	v_add_f32_e32 v42, v42, v43
	v_rcp_f32_e32 v42, v42
	s_sub_i32 s19, s18, 24
	s_ashr_i32 s0, s19, 11
	s_ashr_i32 s1, s0, 31
	s_and_b32 s19, s19, 0x7ff
	s_lshl_b64 s[0:1], s[0:1], 17
	v_mul_f32_e32 v38, v38, v42
	v_lshl_add_u64 v[42:43], v[34:35], 0, s[0:1]
	s_lshl_b32 s20, s19, 2
	v_lshl_add_u64 v[42:43], v[42:43], 0, s[20:21]
	global_store_dword v[42:43], v38, off

.LBB0_1071:
	s_waitcnt vmcnt(0) lgkmcnt(0)
	v_lshlrev_b32_e32 v77, 16, v37
	v_lshlrev_b32_e32 v76, 16, v36
	v_and_b32_e32 v37, 0xffff0000, v37
	v_and_b32_e32 v36, 0xffff0000, v36
	v_pk_add_f32 v[68:69], v[76:77], v[36:37]
	v_lshlrev_b32_e32 v87, 16, v35
	v_lshlrev_b32_e32 v86, 16, v34
	v_and_b32_e32 v35, 0xffff0000, v35
	v_and_b32_e32 v34, 0xffff0000, v34
	v_lshlrev_b32_e32 v46, 16, v39
	v_and_b32_e32 v48, 0xffff0000, v39
	v_add_f32_e32 v39, v68, v69
	v_pk_add_f32 v[68:69], v[86:87], v[34:35]
	v_lshlrev_b32_e32 v42, 16, v40
	v_and_b32_e32 v43, 0xffff0000, v40
	v_lshlrev_b32_e32 v40, 16, v41
	v_and_b32_e32 v41, 0xffff0000, v41
	v_pk_add_f32 v[68:69], v[68:69], v[68:69] op_sel_hi:[0,1]
	v_lshlrev_b32_e32 v44, 16, v38
	v_and_b32_e32 v38, 0xffff0000, v38
	v_add_f32_e32 v49, 0, v39
	v_add_f32_e32 v45, v42, v43
	v_add_f32_e32 v39, v40, v41
	v_mov_b32_e32 v47, v69
	v_pk_add_f32 v[70:71], v[44:45], v[38:39]
	v_pk_add_f32 v[68:69], v[46:47], v[48:49]
	s_min_u32 s0, s24, 29
	v_pk_add_f32 v[68:69], v[70:71], v[68:69]
	s_lshl_b32 s0, s0, 3
	v_add_f32_e32 v39, v68, v69
	s_add_i32 s20, s11, s0
	s_nop 0
	v_add_f32_dpp v39, v39, v39 quad_perm:[1,0,3,2] row_mask:0xf bank_mask:0xf bound_ctrl:1
	s_nop 1
	v_add_f32_dpp v39, v39, v39 quad_perm:[2,3,0,1] row_mask:0xf bank_mask:0xf bound_ctrl:1
	s_nop 1
	v_add_f32_dpp v39, v39, v39 row_half_mirror row_mask:0xf bank_mask:0xf bound_ctrl:1
	s_nop 1
	v_add_f32_dpp v39, v39, v39 row_mirror row_mask:0xf bank_mask:0xf bound_ctrl:1
	s_nop 0
	v_readlane_b32 s21, v39, 16
	v_readlane_b32 s22, v39, 48
	v_readlane_b32 s0, v39, 0
	v_readlane_b32 s1, v39, 32
	v_mov_b32_e32 v68, s21
	v_mov_b32_e32 v69, s22
	v_pk_add_f32 v[68:69], s[0:1], v[68:69]
	s_nop 0
	v_add_f32_e32 v39, v68, v69
	v_fmac_f32_e32 v36, 0xba800000, v39
	v_fmac_f32_e32 v37, 0xba800000, v39
	v_fmac_f32_e32 v77, 0xba800000, v39
	v_fmac_f32_e32 v76, 0xba800000, v39
	v_mov_b32_e32 v88, v77
	v_mov_b32_e32 v89, v37
	v_mov_b32_e32 v77, v36
	v_fmac_f32_e32 v34, 0xba800000, v39
	v_fmac_f32_e32 v35, 0xba800000, v39
	v_fmac_f32_e32 v87, 0xba800000, v39
	v_pk_mul_f32 v[68:69], v[88:89], v[88:89]
	v_pk_mul_f32 v[36:37], v[76:77], v[76:77]
	v_fmac_f32_e32 v86, 0xba800000, v39
	v_mov_b32_e32 v90, v87
	v_mov_b32_e32 v91, v35
	v_mov_b32_e32 v87, v34
	v_pk_mov_b32 v[70:71], v[36:37], v[68:69] op_sel:[1,0]
	v_mov_b32_e32 v37, v69
	v_pk_mul_f32 v[68:69], v[90:91], v[90:91]
	v_pk_mul_f32 v[34:35], v[86:87], v[86:87]
	v_pk_add_f32 v[36:37], v[70:71], v[36:37]
	v_pk_mov_b32 v[70:71], v[34:35], v[68:69] op_sel:[1,0]
	v_mov_b32_e32 v35, v69
	v_pk_add_f32 v[34:35], v[70:71], v[34:35]
	v_fmac_f32_e32 v42, 0xba800000, v39
	v_pk_add_f32 v[34:35], v[34:35], v[34:35] op_sel_hi:[0,1]
	v_fmac_f32_e32 v43, 0xba800000, v39
	v_fmac_f32_e32 v40, 0xba800000, v39
	v_mul_f32_e32 v34, v42, v42
	v_fmac_f32_e32 v41, 0xba800000, v39
	v_pk_fma_f32 v[68:69], v[42:43], v[42:43], v[34:35] op_sel_hi:[1,1,0]
	v_mul_f32_e32 v34, v40, v40
	v_pk_add_f32 v[36:37], v[36:37], v[36:37] op_sel_hi:[0,1]
	v_pk_fma_f32 v[70:71], v[40:41], v[40:41], v[34:35] op_sel_hi:[1,1,0]
	v_fmac_f32_e32 v48, 0xba800000, v39
	v_fmac_f32_e32 v46, 0xba800000, v39
	v_fmac_f32_e32 v38, 0xba800000, v39
	v_fmac_f32_e32 v44, 0xba800000, v39
	v_mul_f32_e32 v68, v44, v44
	v_mul_f32_e32 v70, v38, v38
	v_mul_f32_e32 v36, v46, v46
	v_mul_f32_e32 v34, v48, v48
	v_pk_add_f32 v[68:69], v[68:69], v[70:71]
	v_pk_add_f32 v[34:35], v[36:37], v[34:35]
	v_mov_b32_e32 v47, v48
	v_pk_add_f32 v[34:35], v[68:69], v[34:35]
	s_nop 0
	v_add_f32_e32 v34, v34, v35
	s_nop 1
	v_add_f32_dpp v34, v34, v34 quad_perm:[1,0,3,2] row_mask:0xf bank_mask:0xf bound_ctrl:1
	s_nop 1
	v_add_f32_dpp v34, v34, v34 quad_perm:[2,3,0,1] row_mask:0xf bank_mask:0xf bound_ctrl:1
	s_nop 1
	v_add_f32_dpp v34, v34, v34 row_half_mirror row_mask:0xf bank_mask:0xf bound_ctrl:1
	s_nop 1
	v_add_f32_dpp v34, v34, v34 row_mirror row_mask:0xf bank_mask:0xf bound_ctrl:1
	s_nop 0
	v_readlane_b32 s21, v34, 16
	v_readlane_b32 s22, v34, 48
	v_readlane_b32 s0, v34, 0
	v_readlane_b32 s1, v34, 32
	v_mov_b32_e32 v34, s21
	v_mov_b32_e32 v35, s22
	v_pk_add_f32 v[34:35], s[0:1], v[34:35]
	s_mov_b32 s0, 0xf800000
	v_add_f32_e32 v34, v34, v35
	v_fmamk_f32 v34, v34, 0x3a800000, v82
	s_ashr_i32 s21, s20, 31
	v_mul_f32_e32 v35, 0x4f800000, v34
	v_cmp_gt_f32_e32 vcc, s0, v34
	s_lshl_b64 s[0:1], s[20:21], 11
	s_and_b32 s22, s24, 3
	v_cndmask_b32_e32 v36, v34, v35, vcc
	v_lshl_add_u64 v[34:35], v[54:55], 0, s[0:1]
	global_load_dwordx2 v[68:69], v[34:35], off
	global_load_dwordx2 v[70:71], v[34:35], off offset:512
	global_load_dwordx2 v[72:73], v[34:35], off offset:1024
	global_load_dwordx2 v[74:75], v[34:35], off offset:1536
	v_sqrt_f32_e32 v37, v36
	s_mul_i32 s23, s22, 0x810
	s_add_i32 s23, s87, s23
	v_add_u32_e32 v39, -1, v37
	v_fma_f32 v45, -v39, v37, v36
	v_cmp_ge_f32_e64 s[20:21], 0, v45
	v_add_u32_e32 v45, 1, v37
	s_nop 0
	v_cndmask_b32_e64 v39, v37, v39, s[20:21]
	v_fma_f32 v37, -v45, v37, v36
	v_cmp_lt_f32_e64 s[20:21], 0, v37
	s_nop 1
	v_cndmask_b32_e64 v37, v39, v45, s[20:21]
	v_mul_f32_e32 v39, 0x37800000, v37
	v_cndmask_b32_e32 v37, v37, v39, vcc
	v_cmp_class_f32_e32 vcc, v36, v83
	s_add_i32 s20, s4, s10
	s_ashr_i32 s21, s20, 31
	v_cndmask_b32_e32 v36, v37, v36, vcc
	v_div_scale_f32 v37, s[0:1], v36, v36, 1.0
	v_rcp_f32_e32 v39, v37
	s_lshl_b64 s[0:1], s[20:21], 11
	v_fma_f32 v34, -v37, v39, 1.0
	v_fmac_f32_e32 v39, v34, v39
	v_div_scale_f32 v34, vcc, 1.0, v36, 1.0
	v_mul_f32_e32 v35, v34, v39
	v_fma_f32 v45, -v37, v35, v34
	v_fmac_f32_e32 v35, v45, v39
	v_fma_f32 v34, -v37, v35, v34
	v_div_fmas_f32 v34, v34, v39, v35
	v_div_fixup_f32 v34, v34, v36, 1.0
	v_mov_b32_e32 v45, v38
	v_pk_mul_f32 v[36:37], v[76:77], v[34:35] op_sel_hi:[1,0]
	v_pk_mul_f32 v[76:77], v[88:89], v[34:35] op_sel_hi:[1,0]
	v_pk_mul_f32 v[38:39], v[44:45], v[34:35] op_sel_hi:[1,0]
	v_mov_b32_e32 v44, v168
	v_pk_fma_f32 v[76:77], v[4:5], v[76:77], v[12:13]
	v_pk_fma_f32 v[36:37], v[2:3], v[36:37], v[10:11]
	v_pk_mul_f32 v[86:87], v[86:87], v[34:35] op_sel_hi:[1,0]
	v_pk_mul_f32 v[88:89], v[90:91], v[34:35] op_sel_hi:[1,0]
	v_pk_fma_f32 v[86:87], v[6:7], v[86:87], v[14:15]
	v_pk_fma_f32 v[88:89], v[8:9], v[88:89], v[16:17]
	v_pk_mul_f32 v[42:43], v[42:43], v[34:35] op_sel_hi:[1,0]
	v_pk_mul_f32 v[40:41], v[40:41], v[34:35] op_sel_hi:[1,0]
	v_pk_mul_f32 v[34:35], v[46:47], v[34:35] op_sel_hi:[1,0]
	v_lshl_add_u32 v48, v44, 3, s23
	v_cvt_pk_bf16_f32 v44, v36, v37
	v_cvt_pk_bf16_f32 v45, v76, v77
	v_lshl_add_u64 v[46:47], v[56:57], 0, s[0:1]
	v_pk_fma_f32 v[40:41], v[20:21], v[40:41], v[28:29]
	v_pk_fma_f32 v[42:43], v[18:19], v[42:43], v[26:27]
	global_store_dwordx2 v[46:47], v[44:45], off nt
	ds_write_b64 v48, v[44:45] offset:33024
	v_cvt_pk_bf16_f32 v44, v86, v87
	v_cvt_pk_bf16_f32 v45, v88, v89
	v_pk_fma_f32 v[34:35], v[24:25], v[34:35], v[32:33]
	v_pk_fma_f32 v[38:39], v[22:23], v[38:39], v[30:31]
	global_store_dwordx2 v[46:47], v[44:45], off offset:512 nt
	ds_write_b64 v48, v[44:45] offset:33536
	v_cvt_pk_bf16_f32 v44, v42, v43
	v_cvt_pk_bf16_f32 v45, v40, v41
	global_store_dwordx2 v[46:47], v[44:45], off offset:1024 nt
	ds_write_b64 v48, v[44:45] offset:34048
	v_cvt_pk_bf16_f32 v44, v38, v39
	v_cvt_pk_bf16_f32 v45, v34, v35
	global_store_dwordx2 v[46:47], v[44:45], off offset:1536 nt
	ds_write_b64 v48, v[44:45] offset:34560
	v_med3_f32 v36, v36, s6, v84
	v_med3_f32 v37, v37, s6, v84
	v_mov_b32_e32 v44, 0
	v_cvt_pk_fp8_f32 v44, v36, v37
	v_med3_f32 v36, v76, s6, v84
	v_med3_f32 v37, v77, s6, v84
	v_med3_f32 v45, v86, s6, v84
	v_cvt_pk_fp8_f32 v44, v36, v37 op_sel:[0,0,1]
	v_med3_f32 v46, v87, s6, v84
	v_mov_b32_e32 v47, 0
	v_cvt_pk_fp8_f32 v47, v45, v46
	s_lshl_b64 s[0:1], s[20:21], 10
	v_lshl_add_u64 v[36:37], v[58:59], 0, s[0:1]
	global_store_dword v[36:37], v44, off
	v_med3_f32 v44, v88, s6, v84
	v_med3_f32 v45, v89, s6, v84
	v_cvt_pk_fp8_f32 v47, v44, v45 op_sel:[0,0,1]
	v_med3_f32 v42, v42, s6, v84
	v_med3_f32 v43, v43, s6, v84
	v_mov_b32_e32 v44, 0
	v_cvt_pk_fp8_f32 v44, v42, v43
	v_med3_f32 v38, v38, s6, v84
	v_med3_f32 v39, v39, s6, v84
	v_mov_b32_e32 v42, 0
	v_cvt_pk_fp8_f32 v42, v38, v39
	v_med3_f32 v34, v34, s6, v84
	v_med3_f32 v35, v35, s6, v84
	v_med3_f32 v40, v40, s6, v84
	v_med3_f32 v41, v41, s6, v84
	v_cvt_pk_fp8_f32 v42, v34, v35 op_sel:[0,0,1]
	v_cvt_pk_fp8_f32 v44, v40, v41 op_sel:[0,0,1]
	s_cmp_lg_u32 s22, 3
	global_store_dword v[36:37], v47, off offset:256
	global_store_dword v[36:37], v44, off offset:512
	global_store_dword v[36:37], v42, off offset:768
	s_cbranch_scc1 .LBB0_1070
	v_mov_b32_e32 v76, v168
	s_nop 0
	v_and_b32_e32 v34, 3, v76
	v_mul_u32_u24_e32 v34, 0x810, v34
	v_and_b32_e32 v35, -16, v76
	v_add3_u32 v77, s87, v34, v35
	v_and_b32_e32 v34, 15, v76
	v_mul_u32_u24_e32 v34, 0x810, v34
	v_add3_u32 v85, 0, v34, v35
	ds_read_b128 v[34:37], v77 offset:33024
	ds_read_b128 v[38:41], v85
	s_waitcnt lgkmcnt(0)
	v_mfma_f32_16x16x32_bf16 v[34:37], v[34:37], v[38:41], 0
	ds_read_b128 v[38:41], v77 offset:33088
	ds_read_b128 v[42:45], v85 offset:64
	v_cmp_gt_i32_e32 vcc, 16, v76
	s_waitcnt lgkmcnt(0)
	v_mfma_f32_16x16x32_bf16 v[38:41], v[38:41], v[42:45], 0
	ds_read_b128 v[42:45], v77 offset:33152
	ds_read_b128 v[46:49], v85 offset:128
	s_waitcnt lgkmcnt(0)
	v_mfma_f32_16x16x32_bf16 v[42:45], v[42:45], v[46:49], 0
	ds_read_b128 v[46:49], v77 offset:33216
	ds_read_b128 v[86:89], v85 offset:192
	s_waitcnt lgkmcnt(0)
	v_mfma_f32_16x16x32_bf16 v[46:49], v[46:49], v[86:89], 0
	ds_read_b128 v[86:89], v77 offset:33280
	ds_read_b128 v[90:93], v85 offset:256
	s_waitcnt lgkmcnt(0)
	v_mfma_f32_16x16x32_bf16 v[34:37], v[86:89], v[90:93], v[34:37]
	ds_read_b128 v[86:89], v77 offset:33344
	ds_read_b128 v[90:93], v85 offset:320
	s_waitcnt lgkmcnt(0)
	v_mfma_f32_16x16x32_bf16 v[38:41], v[86:89], v[90:93], v[38:41]
	ds_read_b128 v[86:89], v77 offset:33408
	ds_read_b128 v[90:93], v85 offset:384
	s_waitcnt lgkmcnt(0)
	v_mfma_f32_16x16x32_bf16 v[42:45], v[86:89], v[90:93], v[42:45]
	ds_read_b128 v[86:89], v77 offset:33472
	ds_read_b128 v[90:93], v85 offset:448
	s_waitcnt lgkmcnt(0)
	v_mfma_f32_16x16x32_bf16 v[46:49], v[86:89], v[90:93], v[46:49]
	ds_read_b128 v[86:89], v77 offset:33536
	ds_read_b128 v[90:93], v85 offset:512
	s_waitcnt lgkmcnt(0)
	v_mfma_f32_16x16x32_bf16 v[34:37], v[86:89], v[90:93], v[34:37]
	ds_read_b128 v[86:89], v77 offset:33600
	ds_read_b128 v[90:93], v85 offset:576
	s_waitcnt lgkmcnt(0)
	v_mfma_f32_16x16x32_bf16 v[38:41], v[86:89], v[90:93], v[38:41]
	ds_read_b128 v[86:89], v77 offset:33664
	ds_read_b128 v[90:93], v85 offset:640
	s_waitcnt lgkmcnt(0)
	v_mfma_f32_16x16x32_bf16 v[42:45], v[86:89], v[90:93], v[42:45]
	ds_read_b128 v[86:89], v77 offset:33728
	ds_read_b128 v[90:93], v85 offset:704
	s_waitcnt lgkmcnt(0)
	v_mfma_f32_16x16x32_bf16 v[46:49], v[86:89], v[90:93], v[46:49]
	ds_read_b128 v[86:89], v77 offset:33792
	ds_read_b128 v[90:93], v85 offset:768
	s_waitcnt lgkmcnt(0)
	v_mfma_f32_16x16x32_bf16 v[34:37], v[86:89], v[90:93], v[34:37]
	ds_read_b128 v[86:89], v77 offset:33856
	ds_read_b128 v[90:93], v85 offset:832
	s_waitcnt lgkmcnt(0)
	v_mfma_f32_16x16x32_bf16 v[38:41], v[86:89], v[90:93], v[38:41]
	ds_read_b128 v[86:89], v77 offset:33920
	ds_read_b128 v[90:93], v85 offset:896
	s_waitcnt lgkmcnt(0)
	v_mfma_f32_16x16x32_bf16 v[42:45], v[86:89], v[90:93], v[42:45]
	ds_read_b128 v[86:89], v77 offset:33984
	ds_read_b128 v[90:93], v85 offset:960
	s_waitcnt lgkmcnt(0)
	v_mfma_f32_16x16x32_bf16 v[46:49], v[86:89], v[90:93], v[46:49]
	ds_read_b128 v[86:89], v77 offset:34048
	ds_read_b128 v[90:93], v85 offset:1024
	s_waitcnt lgkmcnt(0)
	v_mfma_f32_16x16x32_bf16 v[34:37], v[86:89], v[90:93], v[34:37]
	ds_read_b128 v[86:89], v77 offset:34112
	ds_read_b128 v[90:93], v85 offset:1088
	s_waitcnt lgkmcnt(0)
	v_mfma_f32_16x16x32_bf16 v[38:41], v[86:89], v[90:93], v[38:41]
	ds_read_b128 v[86:89], v77 offset:34176
	ds_read_b128 v[90:93], v85 offset:1152
	s_waitcnt lgkmcnt(0)
	v_mfma_f32_16x16x32_bf16 v[42:45], v[86:89], v[90:93], v[42:45]
	ds_read_b128 v[86:89], v77 offset:34240
	ds_read_b128 v[90:93], v85 offset:1216
	s_waitcnt lgkmcnt(0)
	v_mfma_f32_16x16x32_bf16 v[46:49], v[86:89], v[90:93], v[46:49]
	ds_read_b128 v[86:89], v77 offset:34304
	ds_read_b128 v[90:93], v85 offset:1280
	s_waitcnt lgkmcnt(0)
	v_mfma_f32_16x16x32_bf16 v[34:37], v[86:89], v[90:93], v[34:37]
	ds_read_b128 v[86:89], v77 offset:34368
	ds_read_b128 v[90:93], v85 offset:1344
	s_waitcnt lgkmcnt(0)
	v_mfma_f32_16x16x32_bf16 v[38:41], v[86:89], v[90:93], v[38:41]
	ds_read_b128 v[86:89], v77 offset:34432
	ds_read_b128 v[90:93], v85 offset:1408
	s_waitcnt lgkmcnt(0)
	v_mfma_f32_16x16x32_bf16 v[42:45], v[86:89], v[90:93], v[42:45]
	ds_read_b128 v[86:89], v77 offset:34496
	ds_read_b128 v[90:93], v85 offset:1472
	s_waitcnt lgkmcnt(0)
	v_mfma_f32_16x16x32_bf16 v[46:49], v[86:89], v[90:93], v[46:49]
	ds_read_b128 v[86:89], v77 offset:34560
	ds_read_b128 v[90:93], v85 offset:1536
	s_waitcnt lgkmcnt(0)
	v_mfma_f32_16x16x32_bf16 v[34:37], v[86:89], v[90:93], v[34:37]
	ds_read_b128 v[86:89], v77 offset:34624
	ds_read_b128 v[90:93], v85 offset:1600
	s_waitcnt lgkmcnt(0)
	v_mfma_f32_16x16x32_bf16 v[38:41], v[86:89], v[90:93], v[38:41]
	ds_read_b128 v[86:89], v77 offset:34688
	ds_read_b128 v[90:93], v85 offset:1664
	s_waitcnt lgkmcnt(0)
	v_mfma_f32_16x16x32_bf16 v[42:45], v[86:89], v[90:93], v[42:45]
	ds_read_b128 v[86:89], v77 offset:34752
	ds_read_b128 v[90:93], v85 offset:1728
	s_waitcnt lgkmcnt(0)
	v_mfma_f32_16x16x32_bf16 v[46:49], v[86:89], v[90:93], v[46:49]
	ds_read_b128 v[86:89], v77 offset:34816
	ds_read_b128 v[90:93], v85 offset:1792
	s_waitcnt lgkmcnt(0)
	v_mfma_f32_16x16x32_bf16 v[34:37], v[86:89], v[90:93], v[34:37]
	ds_read_b128 v[86:89], v77 offset:34880
	ds_read_b128 v[90:93], v85 offset:1856
	s_waitcnt lgkmcnt(0)
	v_mfma_f32_16x16x32_bf16 v[38:41], v[86:89], v[90:93], v[38:41]
	ds_read_b128 v[86:89], v77 offset:34944
	ds_read_b128 v[90:93], v85 offset:1920
	s_waitcnt lgkmcnt(0)
	v_mfma_f32_16x16x32_bf16 v[42:45], v[86:89], v[90:93], v[42:45]
	ds_read_b128 v[86:89], v77 offset:35008
	ds_read_b128 v[90:93], v85 offset:1984
	s_nop 1
	v_pk_add_f32 v[34:35], v[34:35], v[38:39]
	v_ashrrev_i32_e32 v77, 31, v76
	s_waitcnt lgkmcnt(0)
	v_mfma_f32_16x16x32_bf16 v[46:49], v[86:89], v[90:93], v[46:49]
	s_nop 7
	v_pk_add_f32 v[38:39], v[42:43], v[46:47]
	s_nop 0
	v_pk_add_f32 v[38:39], v[34:35], v[38:39]
	v_lshlrev_b64 v[34:35], 13, v[76:77]
	v_lshl_add_u64 v[34:35], s[30:31], 0, v[34:35]
	v_mov_b32_dpp v42, v38 quad_perm:[1,0,3,2] row_mask:0xf bank_mask:0xf bound_ctrl:1
	v_max_f32_e32 v42, v42, v42
	v_max_f32_e32 v42, v38, v42
	s_nop 1
	v_mov_b32_dpp v43, v42 quad_perm:[2,3,0,1] row_mask:0xf bank_mask:0xf bound_ctrl:1
	v_max_f32_e32 v43, v43, v43
	v_max_f32_e32 v42, v42, v43
	s_nop 1
	v_mov_b32_dpp v43, v42 row_half_mirror row_mask:0xf bank_mask:0xf bound_ctrl:1
	v_max_f32_e32 v43, v43, v43
	v_max_f32_e32 v42, v42, v43
	s_nop 1
	v_mov_b32_dpp v43, v42 row_mirror row_mask:0xf bank_mask:0xf bound_ctrl:1
	v_max_f32_e32 v43, v43, v43
	v_max_f32_e32 v42, v42, v43
	v_sub_f32_e32 v38, v38, v42
	v_mul_f32_e32 v38, 0x3fb8aa3b, v38
	v_exp_f32_e32 v38, v38
	s_nop 1
	v_add_f32_dpp v42, v38, v38 quad_perm:[1,0,3,2] row_mask:0xf bank_mask:0xf bound_ctrl:1
	s_nop 1
	v_add_f32_dpp v42, v42, v42 quad_perm:[2,3,0,1] row_mask:0xf bank_mask:0xf bound_ctrl:1
	s_nop 1
	v_add_f32_dpp v42, v42, v42 row_half_mirror row_mask:0xf bank_mask:0xf bound_ctrl:1
	s_nop 1
	v_mov_b32_dpp v43, v42 row_mirror row_mask:0xf bank_mask:0xf bound_ctrl:1
	s_and_saveexec_b64 s[22:23], vcc
	s_cbranch_execz .LBB0_1074
	v_add_f32_e32 v42, v42, v43
	v_rcp_f32_e32 v42, v42
	s_sub_i32 s21, s20, 24
	s_ashr_i32 s0, s21, 11
	s_ashr_i32 s1, s0, 31
	s_and_b32 s21, s21, 0x7ff
	s_lshl_b64 s[0:1], s[0:1], 17
	v_mul_f32_e32 v38, v38, v42
	v_lshl_add_u64 v[42:43], v[34:35], 0, s[0:1]
	s_lshl_b32 s28, s21, 2
	v_lshl_add_u64 v[42:43], v[42:43], 0, s[28:29]
	global_store_dword v[42:43], v38, off

.LBB0_1810:
	s_waitcnt vmcnt(0) lgkmcnt(0)
	v_lshlrev_b32_e32 v77, 16, v37
	v_lshlrev_b32_e32 v76, 16, v36
	v_and_b32_e32 v37, 0xffff0000, v37
	v_and_b32_e32 v36, 0xffff0000, v36
	v_pk_add_f32 v[68:69], v[76:77], v[36:37]
	v_lshlrev_b32_e32 v87, 16, v35
	v_lshlrev_b32_e32 v86, 16, v34
	v_and_b32_e32 v35, 0xffff0000, v35
	v_and_b32_e32 v34, 0xffff0000, v34
	v_lshlrev_b32_e32 v46, 16, v39
	v_and_b32_e32 v48, 0xffff0000, v39
	v_add_f32_e32 v39, v68, v69
	v_pk_add_f32 v[68:69], v[86:87], v[34:35]
	v_lshlrev_b32_e32 v42, 16, v40
	v_and_b32_e32 v43, 0xffff0000, v40
	v_lshlrev_b32_e32 v40, 16, v41
	v_and_b32_e32 v41, 0xffff0000, v41
	v_pk_add_f32 v[68:69], v[68:69], v[68:69] op_sel_hi:[0,1]
	v_lshlrev_b32_e32 v44, 16, v38
	v_and_b32_e32 v38, 0xffff0000, v38
	v_add_f32_e32 v49, 0, v39
	v_add_f32_e32 v45, v42, v43
	v_add_f32_e32 v39, v40, v41
	v_mov_b32_e32 v47, v69
	v_pk_add_f32 v[70:71], v[44:45], v[38:39]
	v_pk_add_f32 v[68:69], v[46:47], v[48:49]
	s_min_u32 s0, s10, 29
	v_pk_add_f32 v[68:69], v[70:71], v[68:69]
	s_lshl_b32 s0, s0, 3
	v_add_f32_e32 v39, v68, v69
	s_add_i32 s22, s9, s0
	s_nop 0
	v_add_f32_dpp v39, v39, v39 quad_perm:[1,0,3,2] row_mask:0xf bank_mask:0xf bound_ctrl:1
	s_nop 1
	v_add_f32_dpp v39, v39, v39 quad_perm:[2,3,0,1] row_mask:0xf bank_mask:0xf bound_ctrl:1
	s_nop 1
	v_add_f32_dpp v39, v39, v39 row_half_mirror row_mask:0xf bank_mask:0xf bound_ctrl:1
	s_nop 1
	v_add_f32_dpp v39, v39, v39 row_mirror row_mask:0xf bank_mask:0xf bound_ctrl:1
	s_nop 0
	v_readlane_b32 s11, v39, 16
	v_readlane_b32 s23, v39, 48
	v_readlane_b32 s0, v39, 0
	v_readlane_b32 s1, v39, 32
	v_mov_b32_e32 v68, s11
	v_mov_b32_e32 v69, s23
	v_pk_add_f32 v[68:69], s[0:1], v[68:69]
	s_nop 0
	v_add_f32_e32 v39, v68, v69
	v_fmac_f32_e32 v36, 0xba800000, v39
	v_fmac_f32_e32 v37, 0xba800000, v39
	v_fmac_f32_e32 v77, 0xba800000, v39
	v_fmac_f32_e32 v76, 0xba800000, v39
	v_mov_b32_e32 v88, v77
	v_mov_b32_e32 v89, v37
	v_mov_b32_e32 v77, v36
	v_fmac_f32_e32 v34, 0xba800000, v39
	v_fmac_f32_e32 v35, 0xba800000, v39
	v_fmac_f32_e32 v87, 0xba800000, v39
	v_pk_mul_f32 v[68:69], v[88:89], v[88:89]
	v_pk_mul_f32 v[36:37], v[76:77], v[76:77]
	v_fmac_f32_e32 v86, 0xba800000, v39
	v_mov_b32_e32 v90, v87
	v_mov_b32_e32 v91, v35
	v_mov_b32_e32 v87, v34
	v_pk_mov_b32 v[70:71], v[36:37], v[68:69] op_sel:[1,0]
	v_mov_b32_e32 v37, v69
	v_pk_mul_f32 v[68:69], v[90:91], v[90:91]
	v_pk_mul_f32 v[34:35], v[86:87], v[86:87]
	v_pk_add_f32 v[36:37], v[70:71], v[36:37]
	v_pk_mov_b32 v[70:71], v[34:35], v[68:69] op_sel:[1,0]
	v_mov_b32_e32 v35, v69
	v_pk_add_f32 v[34:35], v[70:71], v[34:35]
	v_fmac_f32_e32 v42, 0xba800000, v39
	v_pk_add_f32 v[34:35], v[34:35], v[34:35] op_sel_hi:[0,1]
	v_fmac_f32_e32 v43, 0xba800000, v39
	v_fmac_f32_e32 v40, 0xba800000, v39
	v_mul_f32_e32 v34, v42, v42
	v_fmac_f32_e32 v41, 0xba800000, v39
	v_pk_fma_f32 v[68:69], v[42:43], v[42:43], v[34:35] op_sel_hi:[1,1,0]
	v_mul_f32_e32 v34, v40, v40
	v_pk_add_f32 v[36:37], v[36:37], v[36:37] op_sel_hi:[0,1]
	v_pk_fma_f32 v[70:71], v[40:41], v[40:41], v[34:35] op_sel_hi:[1,1,0]
	v_fmac_f32_e32 v48, 0xba800000, v39
	v_fmac_f32_e32 v46, 0xba800000, v39
	v_fmac_f32_e32 v38, 0xba800000, v39
	v_fmac_f32_e32 v44, 0xba800000, v39
	v_mul_f32_e32 v68, v44, v44
	v_mul_f32_e32 v70, v38, v38
	v_mul_f32_e32 v36, v46, v46
	v_mul_f32_e32 v34, v48, v48
	v_pk_add_f32 v[68:69], v[68:69], v[70:71]
	v_pk_add_f32 v[34:35], v[36:37], v[34:35]
	v_mov_b32_e32 v47, v48
	v_pk_add_f32 v[34:35], v[68:69], v[34:35]
	s_nop 0
	v_add_f32_e32 v34, v34, v35
	s_nop 1
	v_add_f32_dpp v34, v34, v34 quad_perm:[1,0,3,2] row_mask:0xf bank_mask:0xf bound_ctrl:1
	s_nop 1
	v_add_f32_dpp v34, v34, v34 quad_perm:[2,3,0,1] row_mask:0xf bank_mask:0xf bound_ctrl:1
	s_nop 1
	v_add_f32_dpp v34, v34, v34 row_half_mirror row_mask:0xf bank_mask:0xf bound_ctrl:1
	s_nop 1
	v_add_f32_dpp v34, v34, v34 row_mirror row_mask:0xf bank_mask:0xf bound_ctrl:1
	s_nop 0
	v_readlane_b32 s11, v34, 16
	v_readlane_b32 s23, v34, 48
	v_readlane_b32 s0, v34, 0
	v_readlane_b32 s1, v34, 32
	v_mov_b32_e32 v34, s11
	v_mov_b32_e32 v35, s23
	v_pk_add_f32 v[34:35], s[0:1], v[34:35]
	s_mov_b32 s0, 0xf800000
	v_add_f32_e32 v34, v34, v35
	v_fmamk_f32 v34, v34, 0x3a800000, v83
	s_ashr_i32 s23, s22, 31
	v_mul_f32_e32 v35, 0x4f800000, v34
	v_cmp_gt_f32_e32 vcc, s0, v34
	s_lshl_b64 s[0:1], s[22:23], 11
	s_and_b32 s11, s10, 3
	v_cndmask_b32_e32 v36, v34, v35, vcc
	v_lshl_add_u64 v[34:35], v[54:55], 0, s[0:1]
	global_load_dwordx2 v[68:69], v[34:35], off
	global_load_dwordx2 v[70:71], v[34:35], off offset:512
	global_load_dwordx2 v[72:73], v[34:35], off offset:1024
	global_load_dwordx2 v[74:75], v[34:35], off offset:1536
	v_sqrt_f32_e32 v37, v36
	s_mul_i32 s26, s11, 0x810
	s_add_i32 s26, s87, s26
	v_add_u32_e32 v39, -1, v37
	v_fma_f32 v45, -v39, v37, v36
	v_cmp_ge_f32_e64 s[22:23], 0, v45
	v_add_u32_e32 v45, 1, v37
	s_nop 0
	v_cndmask_b32_e64 v39, v37, v39, s[22:23]
	v_fma_f32 v37, -v45, v37, v36
	v_cmp_lt_f32_e64 s[22:23], 0, v37
	s_nop 1
	v_cndmask_b32_e64 v37, v39, v45, s[22:23]
	v_mul_f32_e32 v39, 0x37800000, v37
	v_cndmask_b32_e32 v37, v37, v39, vcc
	v_cmp_class_f32_e32 vcc, v36, v84
	s_add_i32 s22, s4, s8
	s_ashr_i32 s23, s22, 31
	v_cndmask_b32_e32 v36, v37, v36, vcc
	v_div_scale_f32 v37, s[0:1], v36, v36, 1.0
	v_rcp_f32_e32 v39, v37
	s_lshl_b64 s[0:1], s[22:23], 11
	v_fma_f32 v34, -v37, v39, 1.0
	v_fmac_f32_e32 v39, v34, v39
	v_div_scale_f32 v34, vcc, 1.0, v36, 1.0
	v_mul_f32_e32 v35, v34, v39
	v_fma_f32 v45, -v37, v35, v34
	v_fmac_f32_e32 v35, v45, v39
	v_fma_f32 v34, -v37, v35, v34
	v_div_fmas_f32 v34, v34, v39, v35
	v_div_fixup_f32 v34, v34, v36, 1.0
	v_mov_b32_e32 v45, v38
	v_pk_mul_f32 v[36:37], v[76:77], v[34:35] op_sel_hi:[1,0]
	v_pk_mul_f32 v[76:77], v[88:89], v[34:35] op_sel_hi:[1,0]
	v_pk_mul_f32 v[38:39], v[44:45], v[34:35] op_sel_hi:[1,0]
	v_mov_b32_e32 v44, v78
	v_pk_fma_f32 v[76:77], v[4:5], v[76:77], v[12:13]
	v_pk_fma_f32 v[36:37], v[2:3], v[36:37], v[10:11]
	v_pk_mul_f32 v[86:87], v[86:87], v[34:35] op_sel_hi:[1,0]
	v_pk_mul_f32 v[88:89], v[90:91], v[34:35] op_sel_hi:[1,0]
	v_pk_fma_f32 v[86:87], v[6:7], v[86:87], v[14:15]
	v_pk_fma_f32 v[88:89], v[8:9], v[88:89], v[16:17]
	v_pk_mul_f32 v[42:43], v[42:43], v[34:35] op_sel_hi:[1,0]
	v_pk_mul_f32 v[40:41], v[40:41], v[34:35] op_sel_hi:[1,0]
	v_pk_mul_f32 v[34:35], v[46:47], v[34:35] op_sel_hi:[1,0]
	v_lshl_add_u32 v48, v44, 3, s26
	v_cvt_pk_bf16_f32 v44, v36, v37
	v_cvt_pk_bf16_f32 v45, v76, v77
	v_lshl_add_u64 v[46:47], v[56:57], 0, s[0:1]
	v_pk_fma_f32 v[40:41], v[20:21], v[40:41], v[28:29]
	v_pk_fma_f32 v[42:43], v[18:19], v[42:43], v[26:27]
	global_store_dwordx2 v[46:47], v[44:45], off nt
	ds_write_b64 v48, v[44:45] offset:33024
	v_cvt_pk_bf16_f32 v44, v86, v87
	v_cvt_pk_bf16_f32 v45, v88, v89
	v_pk_fma_f32 v[34:35], v[24:25], v[34:35], v[32:33]
	v_pk_fma_f32 v[38:39], v[22:23], v[38:39], v[30:31]
	global_store_dwordx2 v[46:47], v[44:45], off offset:512 nt
	ds_write_b64 v48, v[44:45] offset:33536
	v_cvt_pk_bf16_f32 v44, v42, v43
	v_cvt_pk_bf16_f32 v45, v40, v41
	global_store_dwordx2 v[46:47], v[44:45], off offset:1024 nt
	ds_write_b64 v48, v[44:45] offset:34048
	v_cvt_pk_bf16_f32 v44, v38, v39
	v_cvt_pk_bf16_f32 v45, v34, v35
	global_store_dwordx2 v[46:47], v[44:45], off offset:1536 nt
	ds_write_b64 v48, v[44:45] offset:34560
	v_med3_f32 v36, v36, s6, v85
	v_med3_f32 v37, v37, s6, v85
	v_mov_b32_e32 v44, 0
	v_cvt_pk_fp8_f32 v44, v36, v37
	v_med3_f32 v36, v76, s6, v85
	v_med3_f32 v37, v77, s6, v85
	v_med3_f32 v45, v86, s6, v85
	v_cvt_pk_fp8_f32 v44, v36, v37 op_sel:[0,0,1]
	v_med3_f32 v46, v87, s6, v85
	v_mov_b32_e32 v47, 0
	v_cvt_pk_fp8_f32 v47, v45, v46
	s_lshl_b64 s[0:1], s[22:23], 10
	v_lshl_add_u64 v[36:37], v[58:59], 0, s[0:1]
	global_store_dword v[36:37], v44, off
	v_med3_f32 v44, v88, s6, v85
	v_med3_f32 v45, v89, s6, v85
	v_cvt_pk_fp8_f32 v47, v44, v45 op_sel:[0,0,1]
	v_med3_f32 v42, v42, s6, v85
	v_med3_f32 v43, v43, s6, v85
	v_mov_b32_e32 v44, 0
	v_cvt_pk_fp8_f32 v44, v42, v43
	v_med3_f32 v38, v38, s6, v85
	v_med3_f32 v39, v39, s6, v85
	v_mov_b32_e32 v42, 0
	v_cvt_pk_fp8_f32 v42, v38, v39
	v_med3_f32 v34, v34, s6, v85
	v_med3_f32 v35, v35, s6, v85
	v_med3_f32 v40, v40, s6, v85
	v_med3_f32 v41, v41, s6, v85
	v_cvt_pk_fp8_f32 v42, v34, v35 op_sel:[0,0,1]
	v_cvt_pk_fp8_f32 v44, v40, v41 op_sel:[0,0,1]
	s_cmp_lg_u32 s11, 3
	global_store_dword v[36:37], v47, off offset:256
	global_store_dword v[36:37], v44, off offset:512
	global_store_dword v[36:37], v42, off offset:768
	s_cbranch_scc1 .LBB0_1809
	v_mov_b32_e32 v76, v78
	s_nop 0
	v_and_b32_e32 v34, 3, v76
	v_mul_u32_u24_e32 v34, 0x810, v34
	v_and_b32_e32 v35, -16, v76
	v_add3_u32 v77, s87, v34, v35
	v_and_b32_e32 v34, 15, v76
	v_mul_u32_u24_e32 v34, 0x810, v34
	v_add3_u32 v94, 0, v34, v35
	ds_read_b128 v[34:37], v77 offset:33024
	ds_read_b128 v[38:41], v94
	s_waitcnt lgkmcnt(0)
	v_mfma_f32_16x16x32_bf16 v[34:37], v[34:37], v[38:41], 0
	ds_read_b128 v[38:41], v77 offset:33088
	ds_read_b128 v[42:45], v94 offset:64
	v_cmp_gt_i32_e32 vcc, 16, v76
	s_waitcnt lgkmcnt(0)
	v_mfma_f32_16x16x32_bf16 v[38:41], v[38:41], v[42:45], 0
	ds_read_b128 v[42:45], v77 offset:33152
	ds_read_b128 v[46:49], v94 offset:128
	s_waitcnt lgkmcnt(0)
	v_mfma_f32_16x16x32_bf16 v[42:45], v[42:45], v[46:49], 0
	ds_read_b128 v[46:49], v77 offset:33216
	ds_read_b128 v[86:89], v94 offset:192
	s_waitcnt lgkmcnt(0)
	v_mfma_f32_16x16x32_bf16 v[46:49], v[46:49], v[86:89], 0
	ds_read_b128 v[86:89], v77 offset:33280
	ds_read_b128 v[90:93], v94 offset:256
	s_waitcnt lgkmcnt(0)
	v_mfma_f32_16x16x32_bf16 v[34:37], v[86:89], v[90:93], v[34:37]
	ds_read_b128 v[86:89], v77 offset:33344
	ds_read_b128 v[90:93], v94 offset:320
	s_waitcnt lgkmcnt(0)
	v_mfma_f32_16x16x32_bf16 v[38:41], v[86:89], v[90:93], v[38:41]
	ds_read_b128 v[86:89], v77 offset:33408
	ds_read_b128 v[90:93], v94 offset:384
	s_waitcnt lgkmcnt(0)
	v_mfma_f32_16x16x32_bf16 v[42:45], v[86:89], v[90:93], v[42:45]
	ds_read_b128 v[86:89], v77 offset:33472
	ds_read_b128 v[90:93], v94 offset:448
	s_waitcnt lgkmcnt(0)
	v_mfma_f32_16x16x32_bf16 v[46:49], v[86:89], v[90:93], v[46:49]
	ds_read_b128 v[86:89], v77 offset:33536
	ds_read_b128 v[90:93], v94 offset:512
	s_waitcnt lgkmcnt(0)
	v_mfma_f32_16x16x32_bf16 v[34:37], v[86:89], v[90:93], v[34:37]
	ds_read_b128 v[86:89], v77 offset:33600
	ds_read_b128 v[90:93], v94 offset:576
	s_waitcnt lgkmcnt(0)
	v_mfma_f32_16x16x32_bf16 v[38:41], v[86:89], v[90:93], v[38:41]
	ds_read_b128 v[86:89], v77 offset:33664
	ds_read_b128 v[90:93], v94 offset:640
	s_waitcnt lgkmcnt(0)
	v_mfma_f32_16x16x32_bf16 v[42:45], v[86:89], v[90:93], v[42:45]
	ds_read_b128 v[86:89], v77 offset:33728
	ds_read_b128 v[90:93], v94 offset:704
	s_waitcnt lgkmcnt(0)
	v_mfma_f32_16x16x32_bf16 v[46:49], v[86:89], v[90:93], v[46:49]
	ds_read_b128 v[86:89], v77 offset:33792
	ds_read_b128 v[90:93], v94 offset:768
	s_waitcnt lgkmcnt(0)
	v_mfma_f32_16x16x32_bf16 v[34:37], v[86:89], v[90:93], v[34:37]
	ds_read_b128 v[86:89], v77 offset:33856
	ds_read_b128 v[90:93], v94 offset:832
	s_waitcnt lgkmcnt(0)
	v_mfma_f32_16x16x32_bf16 v[38:41], v[86:89], v[90:93], v[38:41]
	ds_read_b128 v[86:89], v77 offset:33920
	ds_read_b128 v[90:93], v94 offset:896
	s_waitcnt lgkmcnt(0)
	v_mfma_f32_16x16x32_bf16 v[42:45], v[86:89], v[90:93], v[42:45]
	ds_read_b128 v[86:89], v77 offset:33984
	ds_read_b128 v[90:93], v94 offset:960
	s_waitcnt lgkmcnt(0)
	v_mfma_f32_16x16x32_bf16 v[46:49], v[86:89], v[90:93], v[46:49]
	ds_read_b128 v[86:89], v77 offset:34048
	ds_read_b128 v[90:93], v94 offset:1024
	s_waitcnt lgkmcnt(0)
	v_mfma_f32_16x16x32_bf16 v[34:37], v[86:89], v[90:93], v[34:37]
	ds_read_b128 v[86:89], v77 offset:34112
	ds_read_b128 v[90:93], v94 offset:1088
	s_waitcnt lgkmcnt(0)
	v_mfma_f32_16x16x32_bf16 v[38:41], v[86:89], v[90:93], v[38:41]
	ds_read_b128 v[86:89], v77 offset:34176
	ds_read_b128 v[90:93], v94 offset:1152
	s_waitcnt lgkmcnt(0)
	v_mfma_f32_16x16x32_bf16 v[42:45], v[86:89], v[90:93], v[42:45]
	ds_read_b128 v[86:89], v77 offset:34240
	ds_read_b128 v[90:93], v94 offset:1216
	s_waitcnt lgkmcnt(0)
	v_mfma_f32_16x16x32_bf16 v[46:49], v[86:89], v[90:93], v[46:49]
	ds_read_b128 v[86:89], v77 offset:34304
	ds_read_b128 v[90:93], v94 offset:1280
	s_waitcnt lgkmcnt(0)
	v_mfma_f32_16x16x32_bf16 v[34:37], v[86:89], v[90:93], v[34:37]
	ds_read_b128 v[86:89], v77 offset:34368
	ds_read_b128 v[90:93], v94 offset:1344
	s_waitcnt lgkmcnt(0)
	v_mfma_f32_16x16x32_bf16 v[38:41], v[86:89], v[90:93], v[38:41]
	ds_read_b128 v[86:89], v77 offset:34432
	ds_read_b128 v[90:93], v94 offset:1408
	s_waitcnt lgkmcnt(0)
	v_mfma_f32_16x16x32_bf16 v[42:45], v[86:89], v[90:93], v[42:45]
	ds_read_b128 v[86:89], v77 offset:34496
	ds_read_b128 v[90:93], v94 offset:1472
	s_waitcnt lgkmcnt(0)
	v_mfma_f32_16x16x32_bf16 v[46:49], v[86:89], v[90:93], v[46:49]
	ds_read_b128 v[86:89], v77 offset:34560
	ds_read_b128 v[90:93], v94 offset:1536
	s_waitcnt lgkmcnt(0)
	v_mfma_f32_16x16x32_bf16 v[34:37], v[86:89], v[90:93], v[34:37]
	ds_read_b128 v[86:89], v77 offset:34624
	ds_read_b128 v[90:93], v94 offset:1600
	s_waitcnt lgkmcnt(0)
	v_mfma_f32_16x16x32_bf16 v[38:41], v[86:89], v[90:93], v[38:41]
	ds_read_b128 v[86:89], v77 offset:34688
	ds_read_b128 v[90:93], v94 offset:1664
	s_waitcnt lgkmcnt(0)
	v_mfma_f32_16x16x32_bf16 v[42:45], v[86:89], v[90:93], v[42:45]
	ds_read_b128 v[86:89], v77 offset:34752
	ds_read_b128 v[90:93], v94 offset:1728
	s_waitcnt lgkmcnt(0)
	v_mfma_f32_16x16x32_bf16 v[46:49], v[86:89], v[90:93], v[46:49]
	ds_read_b128 v[86:89], v77 offset:34816
	ds_read_b128 v[90:93], v94 offset:1792
	s_waitcnt lgkmcnt(0)
	v_mfma_f32_16x16x32_bf16 v[34:37], v[86:89], v[90:93], v[34:37]
	ds_read_b128 v[86:89], v77 offset:34880
	ds_read_b128 v[90:93], v94 offset:1856
	s_waitcnt lgkmcnt(0)
	v_mfma_f32_16x16x32_bf16 v[38:41], v[86:89], v[90:93], v[38:41]
	ds_read_b128 v[86:89], v77 offset:34944
	ds_read_b128 v[90:93], v94 offset:1920
	s_waitcnt lgkmcnt(0)
	v_mfma_f32_16x16x32_bf16 v[42:45], v[86:89], v[90:93], v[42:45]
	ds_read_b128 v[86:89], v77 offset:35008
	ds_read_b128 v[90:93], v94 offset:1984
	s_nop 1
	v_pk_add_f32 v[34:35], v[34:35], v[38:39]
	v_ashrrev_i32_e32 v77, 31, v76
	s_waitcnt lgkmcnt(0)
	v_mfma_f32_16x16x32_bf16 v[46:49], v[86:89], v[90:93], v[46:49]
	s_nop 7
	v_pk_add_f32 v[38:39], v[42:43], v[46:47]
	s_nop 0
	v_pk_add_f32 v[38:39], v[34:35], v[38:39]
	v_lshlrev_b64 v[34:35], 13, v[76:77]
	v_lshl_add_u64 v[34:35], s[30:31], 0, v[34:35]
	v_mov_b32_dpp v42, v38 quad_perm:[1,0,3,2] row_mask:0xf bank_mask:0xf bound_ctrl:1
	v_max_f32_e32 v42, v42, v42
	v_max_f32_e32 v42, v38, v42
	s_nop 1
	v_mov_b32_dpp v43, v42 quad_perm:[2,3,0,1] row_mask:0xf bank_mask:0xf bound_ctrl:1
	v_max_f32_e32 v43, v43, v43
	v_max_f32_e32 v42, v42, v43
	s_nop 1
	v_mov_b32_dpp v43, v42 row_half_mirror row_mask:0xf bank_mask:0xf bound_ctrl:1
	v_max_f32_e32 v43, v43, v43
	v_max_f32_e32 v42, v42, v43
	s_nop 1
	v_mov_b32_dpp v43, v42 row_mirror row_mask:0xf bank_mask:0xf bound_ctrl:1
	v_max_f32_e32 v43, v43, v43
	v_max_f32_e32 v42, v42, v43
	v_sub_f32_e32 v38, v38, v42
	v_mul_f32_e32 v38, 0x3fb8aa3b, v38
	v_exp_f32_e32 v38, v38
	s_nop 1
	v_add_f32_dpp v42, v38, v38 quad_perm:[1,0,3,2] row_mask:0xf bank_mask:0xf bound_ctrl:1
	s_nop 1
	v_add_f32_dpp v42, v42, v42 quad_perm:[2,3,0,1] row_mask:0xf bank_mask:0xf bound_ctrl:1
	s_nop 1
	v_add_f32_dpp v42, v42, v42 row_half_mirror row_mask:0xf bank_mask:0xf bound_ctrl:1
	s_nop 1
	v_mov_b32_dpp v43, v42 row_mirror row_mask:0xf bank_mask:0xf bound_ctrl:1
	s_and_saveexec_b64 s[34:35], vcc
	s_cbranch_execz .LBB0_1813
	v_add_f32_e32 v42, v42, v43
	v_rcp_f32_e32 v42, v42
	s_sub_i32 s11, s22, 24
	s_ashr_i32 s0, s11, 11
	s_ashr_i32 s1, s0, 31
	s_and_b32 s11, s11, 0x7ff
	s_lshl_b64 s[0:1], s[0:1], 17
	v_mul_f32_e32 v38, v38, v42
	v_lshl_add_u64 v[42:43], v[34:35], 0, s[0:1]
	s_lshl_b32 s26, s11, 2
	v_lshl_add_u64 v[42:43], v[42:43], 0, s[26:27]
	global_store_dword v[42:43], v38, off

.LBB0_2519:
	s_waitcnt vmcnt(0) lgkmcnt(0)
	v_lshlrev_b32_e32 v77, 16, v37
	v_lshlrev_b32_e32 v76, 16, v36
	v_and_b32_e32 v37, 0xffff0000, v37
	v_and_b32_e32 v36, 0xffff0000, v36
	v_pk_add_f32 v[68:69], v[76:77], v[36:37]
	v_lshlrev_b32_e32 v87, 16, v35
	v_lshlrev_b32_e32 v86, 16, v34
	v_and_b32_e32 v35, 0xffff0000, v35
	v_and_b32_e32 v34, 0xffff0000, v34
	v_lshlrev_b32_e32 v46, 16, v39
	v_and_b32_e32 v48, 0xffff0000, v39
	v_add_f32_e32 v39, v68, v69
	v_pk_add_f32 v[68:69], v[86:87], v[34:35]
	v_lshlrev_b32_e32 v42, 16, v40
	v_and_b32_e32 v43, 0xffff0000, v40
	v_lshlrev_b32_e32 v40, 16, v41
	v_and_b32_e32 v41, 0xffff0000, v41
	v_pk_add_f32 v[68:69], v[68:69], v[68:69] op_sel_hi:[0,1]
	v_lshlrev_b32_e32 v44, 16, v38
	v_and_b32_e32 v38, 0xffff0000, v38
	v_add_f32_e32 v49, 0, v39
	v_add_f32_e32 v45, v42, v43
	v_add_f32_e32 v39, v40, v41
	v_mov_b32_e32 v47, v69
	v_pk_add_f32 v[70:71], v[44:45], v[38:39]
	v_pk_add_f32 v[68:69], v[46:47], v[48:49]
	s_min_u32 s0, s30, 29
	v_pk_add_f32 v[68:69], v[70:71], v[68:69]
	s_lshl_b32 s0, s0, 3
	v_add_f32_e32 v39, v68, v69
	s_add_i32 s18, s29, s0
	s_nop 0
	v_add_f32_dpp v39, v39, v39 quad_perm:[1,0,3,2] row_mask:0xf bank_mask:0xf bound_ctrl:1
	s_nop 1
	v_add_f32_dpp v39, v39, v39 quad_perm:[2,3,0,1] row_mask:0xf bank_mask:0xf bound_ctrl:1
	s_nop 1
	v_add_f32_dpp v39, v39, v39 row_half_mirror row_mask:0xf bank_mask:0xf bound_ctrl:1
	s_nop 1
	v_add_f32_dpp v39, v39, v39 row_mirror row_mask:0xf bank_mask:0xf bound_ctrl:1
	s_nop 0
	v_readlane_b32 s19, v39, 16
	v_readlane_b32 s22, v39, 48
	v_readlane_b32 s0, v39, 0
	v_readlane_b32 s1, v39, 32
	v_mov_b32_e32 v68, s19
	v_mov_b32_e32 v69, s22
	v_pk_add_f32 v[68:69], s[0:1], v[68:69]
	s_nop 0
	v_add_f32_e32 v39, v68, v69
	v_fmac_f32_e32 v36, 0xba800000, v39
	v_fmac_f32_e32 v37, 0xba800000, v39
	v_fmac_f32_e32 v77, 0xba800000, v39
	v_fmac_f32_e32 v76, 0xba800000, v39
	v_mov_b32_e32 v88, v77
	v_mov_b32_e32 v89, v37
	v_mov_b32_e32 v77, v36
	v_fmac_f32_e32 v34, 0xba800000, v39
	v_fmac_f32_e32 v35, 0xba800000, v39
	v_fmac_f32_e32 v87, 0xba800000, v39
	v_pk_mul_f32 v[68:69], v[88:89], v[88:89]
	v_pk_mul_f32 v[36:37], v[76:77], v[76:77]
	v_fmac_f32_e32 v86, 0xba800000, v39
	v_mov_b32_e32 v90, v87
	v_mov_b32_e32 v91, v35
	v_mov_b32_e32 v87, v34
	v_pk_mov_b32 v[70:71], v[36:37], v[68:69] op_sel:[1,0]
	v_mov_b32_e32 v37, v69
	v_pk_mul_f32 v[68:69], v[90:91], v[90:91]
	v_pk_mul_f32 v[34:35], v[86:87], v[86:87]
	v_pk_add_f32 v[36:37], v[70:71], v[36:37]
	v_pk_mov_b32 v[70:71], v[34:35], v[68:69] op_sel:[1,0]
	v_mov_b32_e32 v35, v69
	v_pk_add_f32 v[34:35], v[70:71], v[34:35]
	v_fmac_f32_e32 v42, 0xba800000, v39
	v_pk_add_f32 v[34:35], v[34:35], v[34:35] op_sel_hi:[0,1]
	v_fmac_f32_e32 v43, 0xba800000, v39
	v_fmac_f32_e32 v40, 0xba800000, v39
	v_mul_f32_e32 v34, v42, v42
	v_fmac_f32_e32 v41, 0xba800000, v39
	v_pk_fma_f32 v[68:69], v[42:43], v[42:43], v[34:35] op_sel_hi:[1,1,0]
	v_mul_f32_e32 v34, v40, v40
	v_pk_add_f32 v[36:37], v[36:37], v[36:37] op_sel_hi:[0,1]
	v_pk_fma_f32 v[70:71], v[40:41], v[40:41], v[34:35] op_sel_hi:[1,1,0]
	v_fmac_f32_e32 v48, 0xba800000, v39
	v_fmac_f32_e32 v46, 0xba800000, v39
	v_fmac_f32_e32 v38, 0xba800000, v39
	v_fmac_f32_e32 v44, 0xba800000, v39
	v_mul_f32_e32 v68, v44, v44
	v_mul_f32_e32 v70, v38, v38
	v_mul_f32_e32 v36, v46, v46
	v_mul_f32_e32 v34, v48, v48
	v_pk_add_f32 v[68:69], v[68:69], v[70:71]
	v_pk_add_f32 v[34:35], v[36:37], v[34:35]
	v_mov_b32_e32 v47, v48
	v_pk_add_f32 v[34:35], v[68:69], v[34:35]
	s_nop 0
	v_add_f32_e32 v34, v34, v35
	s_nop 1
	v_add_f32_dpp v34, v34, v34 quad_perm:[1,0,3,2] row_mask:0xf bank_mask:0xf bound_ctrl:1
	s_nop 1
	v_add_f32_dpp v34, v34, v34 quad_perm:[2,3,0,1] row_mask:0xf bank_mask:0xf bound_ctrl:1
	s_nop 1
	v_add_f32_dpp v34, v34, v34 row_half_mirror row_mask:0xf bank_mask:0xf bound_ctrl:1
	s_nop 1
	v_add_f32_dpp v34, v34, v34 row_mirror row_mask:0xf bank_mask:0xf bound_ctrl:1
	s_nop 0
	v_readlane_b32 s19, v34, 16
	v_readlane_b32 s22, v34, 48
	v_readlane_b32 s0, v34, 0
	v_readlane_b32 s1, v34, 32
	v_mov_b32_e32 v34, s19
	v_mov_b32_e32 v35, s22
	v_pk_add_f32 v[34:35], s[0:1], v[34:35]
	s_mov_b32 s0, 0xf800000
	v_add_f32_e32 v34, v34, v35
	v_fmamk_f32 v34, v34, 0x3a800000, v83
	s_ashr_i32 s19, s18, 31
	v_mul_f32_e32 v35, 0x4f800000, v34
	v_cmp_gt_f32_e32 vcc, s0, v34
	s_lshl_b64 s[0:1], s[18:19], 11
	s_and_b32 s22, s30, 3
	v_cndmask_b32_e32 v36, v34, v35, vcc
	v_lshl_add_u64 v[34:35], v[54:55], 0, s[0:1]
	global_load_dwordx2 v[68:69], v[34:35], off
	global_load_dwordx2 v[70:71], v[34:35], off offset:512
	global_load_dwordx2 v[72:73], v[34:35], off offset:1024
	global_load_dwordx2 v[74:75], v[34:35], off offset:1536
	v_sqrt_f32_e32 v37, v36
	s_mul_i32 s26, s22, 0x810
	s_add_i32 s26, s87, s26
	v_add_u32_e32 v39, -1, v37
	v_fma_f32 v45, -v39, v37, v36
	v_cmp_ge_f32_e64 s[18:19], 0, v45
	v_add_u32_e32 v45, 1, v37
	s_nop 0
	v_cndmask_b32_e64 v39, v37, v39, s[18:19]
	v_fma_f32 v37, -v45, v37, v36
	v_cmp_lt_f32_e64 s[18:19], 0, v37
	s_nop 1
	v_cndmask_b32_e64 v37, v39, v45, s[18:19]
	v_mul_f32_e32 v39, 0x37800000, v37
	v_cndmask_b32_e32 v37, v37, v39, vcc
	v_cmp_class_f32_e32 vcc, v36, v84
	s_add_i32 s18, s4, s28
	s_ashr_i32 s19, s18, 31
	v_cndmask_b32_e32 v36, v37, v36, vcc
	v_div_scale_f32 v37, s[0:1], v36, v36, 1.0
	v_rcp_f32_e32 v39, v37
	s_lshl_b64 s[0:1], s[18:19], 11
	v_fma_f32 v34, -v37, v39, 1.0
	v_fmac_f32_e32 v39, v34, v39
	v_div_scale_f32 v34, vcc, 1.0, v36, 1.0
	v_mul_f32_e32 v35, v34, v39
	v_fma_f32 v45, -v37, v35, v34
	v_fmac_f32_e32 v35, v45, v39
	v_fma_f32 v34, -v37, v35, v34
	v_div_fmas_f32 v34, v34, v39, v35
	v_div_fixup_f32 v34, v34, v36, 1.0
	v_mov_b32_e32 v45, v38
	v_pk_mul_f32 v[36:37], v[76:77], v[34:35] op_sel_hi:[1,0]
	v_pk_mul_f32 v[76:77], v[88:89], v[34:35] op_sel_hi:[1,0]
	v_pk_mul_f32 v[38:39], v[44:45], v[34:35] op_sel_hi:[1,0]
	v_mov_b32_e32 v44, v78
	v_pk_fma_f32 v[76:77], v[4:5], v[76:77], v[12:13]
	v_pk_fma_f32 v[36:37], v[2:3], v[36:37], v[10:11]
	v_pk_mul_f32 v[86:87], v[86:87], v[34:35] op_sel_hi:[1,0]
	v_pk_mul_f32 v[88:89], v[90:91], v[34:35] op_sel_hi:[1,0]
	v_pk_fma_f32 v[86:87], v[6:7], v[86:87], v[14:15]
	v_pk_fma_f32 v[88:89], v[8:9], v[88:89], v[16:17]
	v_pk_mul_f32 v[42:43], v[42:43], v[34:35] op_sel_hi:[1,0]
	v_pk_mul_f32 v[40:41], v[40:41], v[34:35] op_sel_hi:[1,0]
	v_pk_mul_f32 v[34:35], v[46:47], v[34:35] op_sel_hi:[1,0]
	v_lshl_add_u32 v48, v44, 3, s26
	v_cvt_pk_bf16_f32 v44, v36, v37
	v_cvt_pk_bf16_f32 v45, v76, v77
	v_lshl_add_u64 v[46:47], v[56:57], 0, s[0:1]
	v_pk_fma_f32 v[40:41], v[20:21], v[40:41], v[28:29]
	v_pk_fma_f32 v[42:43], v[18:19], v[42:43], v[26:27]
	global_store_dwordx2 v[46:47], v[44:45], off nt
	ds_write_b64 v48, v[44:45] offset:33024
	v_cvt_pk_bf16_f32 v44, v86, v87
	v_cvt_pk_bf16_f32 v45, v88, v89
	v_pk_fma_f32 v[34:35], v[24:25], v[34:35], v[32:33]
	v_pk_fma_f32 v[38:39], v[22:23], v[38:39], v[30:31]
	global_store_dwordx2 v[46:47], v[44:45], off offset:512 nt
	ds_write_b64 v48, v[44:45] offset:33536
	v_cvt_pk_bf16_f32 v44, v42, v43
	v_cvt_pk_bf16_f32 v45, v40, v41
	global_store_dwordx2 v[46:47], v[44:45], off offset:1024 nt
	ds_write_b64 v48, v[44:45] offset:34048
	v_cvt_pk_bf16_f32 v44, v38, v39
	v_cvt_pk_bf16_f32 v45, v34, v35
	global_store_dwordx2 v[46:47], v[44:45], off offset:1536 nt
	ds_write_b64 v48, v[44:45] offset:34560
	v_med3_f32 v36, v36, s8, v85
	v_med3_f32 v37, v37, s8, v85
	v_mov_b32_e32 v44, 0
	v_cvt_pk_fp8_f32 v44, v36, v37
	v_med3_f32 v36, v76, s8, v85
	v_med3_f32 v37, v77, s8, v85
	v_med3_f32 v45, v86, s8, v85
	v_cvt_pk_fp8_f32 v44, v36, v37 op_sel:[0,0,1]
	v_med3_f32 v46, v87, s8, v85
	v_mov_b32_e32 v47, 0
	v_cvt_pk_fp8_f32 v47, v45, v46
	s_lshl_b64 s[0:1], s[18:19], 10
	v_lshl_add_u64 v[36:37], v[58:59], 0, s[0:1]
	global_store_dword v[36:37], v44, off
	v_med3_f32 v44, v88, s8, v85
	v_med3_f32 v45, v89, s8, v85
	v_cvt_pk_fp8_f32 v47, v44, v45 op_sel:[0,0,1]
	v_med3_f32 v42, v42, s8, v85
	v_med3_f32 v43, v43, s8, v85
	v_mov_b32_e32 v44, 0
	v_cvt_pk_fp8_f32 v44, v42, v43
	v_med3_f32 v38, v38, s8, v85
	v_med3_f32 v39, v39, s8, v85
	v_mov_b32_e32 v42, 0
	v_cvt_pk_fp8_f32 v42, v38, v39
	v_med3_f32 v34, v34, s8, v85
	v_med3_f32 v35, v35, s8, v85
	v_med3_f32 v40, v40, s8, v85
	v_med3_f32 v41, v41, s8, v85
	v_cvt_pk_fp8_f32 v42, v34, v35 op_sel:[0,0,1]
	v_cvt_pk_fp8_f32 v44, v40, v41 op_sel:[0,0,1]
	s_cmp_lg_u32 s22, 3
	global_store_dword v[36:37], v47, off offset:256
	global_store_dword v[36:37], v44, off offset:512
	global_store_dword v[36:37], v42, off offset:768
	s_cbranch_scc1 .LBB0_2518
	v_mov_b32_e32 v76, v78
	s_nop 0
	v_and_b32_e32 v34, 3, v76
	v_mul_u32_u24_e32 v34, 0x810, v34
	v_and_b32_e32 v35, -16, v76
	v_add3_u32 v77, s87, v34, v35
	v_and_b32_e32 v34, 15, v76
	v_mul_u32_u24_e32 v34, 0x810, v34
	v_add3_u32 v94, 0, v34, v35
	ds_read_b128 v[34:37], v77 offset:33024
	ds_read_b128 v[38:41], v94
	s_waitcnt lgkmcnt(0)
	v_mfma_f32_16x16x32_bf16 v[34:37], v[34:37], v[38:41], 0
	ds_read_b128 v[38:41], v77 offset:33088
	ds_read_b128 v[42:45], v94 offset:64
	v_cmp_gt_i32_e32 vcc, 16, v76
	s_waitcnt lgkmcnt(0)
	v_mfma_f32_16x16x32_bf16 v[38:41], v[38:41], v[42:45], 0
	ds_read_b128 v[42:45], v77 offset:33152
	ds_read_b128 v[46:49], v94 offset:128
	s_waitcnt lgkmcnt(0)
	v_mfma_f32_16x16x32_bf16 v[42:45], v[42:45], v[46:49], 0
	ds_read_b128 v[46:49], v77 offset:33216
	ds_read_b128 v[86:89], v94 offset:192
	s_waitcnt lgkmcnt(0)
	v_mfma_f32_16x16x32_bf16 v[46:49], v[46:49], v[86:89], 0
	ds_read_b128 v[86:89], v77 offset:33280
	ds_read_b128 v[90:93], v94 offset:256
	s_waitcnt lgkmcnt(0)
	v_mfma_f32_16x16x32_bf16 v[34:37], v[86:89], v[90:93], v[34:37]
	ds_read_b128 v[86:89], v77 offset:33344
	ds_read_b128 v[90:93], v94 offset:320
	s_waitcnt lgkmcnt(0)
	v_mfma_f32_16x16x32_bf16 v[38:41], v[86:89], v[90:93], v[38:41]
	ds_read_b128 v[86:89], v77 offset:33408
	ds_read_b128 v[90:93], v94 offset:384
	s_waitcnt lgkmcnt(0)
	v_mfma_f32_16x16x32_bf16 v[42:45], v[86:89], v[90:93], v[42:45]
	ds_read_b128 v[86:89], v77 offset:33472
	ds_read_b128 v[90:93], v94 offset:448
	s_waitcnt lgkmcnt(0)
	v_mfma_f32_16x16x32_bf16 v[46:49], v[86:89], v[90:93], v[46:49]
	ds_read_b128 v[86:89], v77 offset:33536
	ds_read_b128 v[90:93], v94 offset:512
	s_waitcnt lgkmcnt(0)
	v_mfma_f32_16x16x32_bf16 v[34:37], v[86:89], v[90:93], v[34:37]
	ds_read_b128 v[86:89], v77 offset:33600
	ds_read_b128 v[90:93], v94 offset:576
	s_waitcnt lgkmcnt(0)
	v_mfma_f32_16x16x32_bf16 v[38:41], v[86:89], v[90:93], v[38:41]
	ds_read_b128 v[86:89], v77 offset:33664
	ds_read_b128 v[90:93], v94 offset:640
	s_waitcnt lgkmcnt(0)
	v_mfma_f32_16x16x32_bf16 v[42:45], v[86:89], v[90:93], v[42:45]
	ds_read_b128 v[86:89], v77 offset:33728
	ds_read_b128 v[90:93], v94 offset:704
	s_waitcnt lgkmcnt(0)
	v_mfma_f32_16x16x32_bf16 v[46:49], v[86:89], v[90:93], v[46:49]
	ds_read_b128 v[86:89], v77 offset:33792
	ds_read_b128 v[90:93], v94 offset:768
	s_waitcnt lgkmcnt(0)
	v_mfma_f32_16x16x32_bf16 v[34:37], v[86:89], v[90:93], v[34:37]
	ds_read_b128 v[86:89], v77 offset:33856
	ds_read_b128 v[90:93], v94 offset:832
	s_waitcnt lgkmcnt(0)
	v_mfma_f32_16x16x32_bf16 v[38:41], v[86:89], v[90:93], v[38:41]
	ds_read_b128 v[86:89], v77 offset:33920
	ds_read_b128 v[90:93], v94 offset:896
	s_waitcnt lgkmcnt(0)
	v_mfma_f32_16x16x32_bf16 v[42:45], v[86:89], v[90:93], v[42:45]
	ds_read_b128 v[86:89], v77 offset:33984
	ds_read_b128 v[90:93], v94 offset:960
	s_waitcnt lgkmcnt(0)
	v_mfma_f32_16x16x32_bf16 v[46:49], v[86:89], v[90:93], v[46:49]
	ds_read_b128 v[86:89], v77 offset:34048
	ds_read_b128 v[90:93], v94 offset:1024
	s_waitcnt lgkmcnt(0)
	v_mfma_f32_16x16x32_bf16 v[34:37], v[86:89], v[90:93], v[34:37]
	ds_read_b128 v[86:89], v77 offset:34112
	ds_read_b128 v[90:93], v94 offset:1088
	s_waitcnt lgkmcnt(0)
	v_mfma_f32_16x16x32_bf16 v[38:41], v[86:89], v[90:93], v[38:41]
	ds_read_b128 v[86:89], v77 offset:34176
	ds_read_b128 v[90:93], v94 offset:1152
	s_waitcnt lgkmcnt(0)
	v_mfma_f32_16x16x32_bf16 v[42:45], v[86:89], v[90:93], v[42:45]
	ds_read_b128 v[86:89], v77 offset:34240
	ds_read_b128 v[90:93], v94 offset:1216
	s_waitcnt lgkmcnt(0)
	v_mfma_f32_16x16x32_bf16 v[46:49], v[86:89], v[90:93], v[46:49]
	ds_read_b128 v[86:89], v77 offset:34304
	ds_read_b128 v[90:93], v94 offset:1280
	s_waitcnt lgkmcnt(0)
	v_mfma_f32_16x16x32_bf16 v[34:37], v[86:89], v[90:93], v[34:37]
	ds_read_b128 v[86:89], v77 offset:34368
	ds_read_b128 v[90:93], v94 offset:1344
	s_waitcnt lgkmcnt(0)
	v_mfma_f32_16x16x32_bf16 v[38:41], v[86:89], v[90:93], v[38:41]
	ds_read_b128 v[86:89], v77 offset:34432
	ds_read_b128 v[90:93], v94 offset:1408
	s_waitcnt lgkmcnt(0)
	v_mfma_f32_16x16x32_bf16 v[42:45], v[86:89], v[90:93], v[42:45]
	ds_read_b128 v[86:89], v77 offset:34496
	ds_read_b128 v[90:93], v94 offset:1472
	s_waitcnt lgkmcnt(0)
	v_mfma_f32_16x16x32_bf16 v[46:49], v[86:89], v[90:93], v[46:49]
	ds_read_b128 v[86:89], v77 offset:34560
	ds_read_b128 v[90:93], v94 offset:1536
	s_waitcnt lgkmcnt(0)
	v_mfma_f32_16x16x32_bf16 v[34:37], v[86:89], v[90:93], v[34:37]
	ds_read_b128 v[86:89], v77 offset:34624
	ds_read_b128 v[90:93], v94 offset:1600
	s_waitcnt lgkmcnt(0)
	v_mfma_f32_16x16x32_bf16 v[38:41], v[86:89], v[90:93], v[38:41]
	ds_read_b128 v[86:89], v77 offset:34688
	ds_read_b128 v[90:93], v94 offset:1664
	s_waitcnt lgkmcnt(0)
	v_mfma_f32_16x16x32_bf16 v[42:45], v[86:89], v[90:93], v[42:45]
	ds_read_b128 v[86:89], v77 offset:34752
	ds_read_b128 v[90:93], v94 offset:1728
	s_waitcnt lgkmcnt(0)
	v_mfma_f32_16x16x32_bf16 v[46:49], v[86:89], v[90:93], v[46:49]
	ds_read_b128 v[86:89], v77 offset:34816
	ds_read_b128 v[90:93], v94 offset:1792
	s_waitcnt lgkmcnt(0)
	v_mfma_f32_16x16x32_bf16 v[34:37], v[86:89], v[90:93], v[34:37]
	ds_read_b128 v[86:89], v77 offset:34880
	ds_read_b128 v[90:93], v94 offset:1856
	s_waitcnt lgkmcnt(0)
	v_mfma_f32_16x16x32_bf16 v[38:41], v[86:89], v[90:93], v[38:41]
	ds_read_b128 v[86:89], v77 offset:34944
	ds_read_b128 v[90:93], v94 offset:1920
	s_waitcnt lgkmcnt(0)
	v_mfma_f32_16x16x32_bf16 v[42:45], v[86:89], v[90:93], v[42:45]
	ds_read_b128 v[86:89], v77 offset:35008
	ds_read_b128 v[90:93], v94 offset:1984
	s_nop 1
	v_pk_add_f32 v[34:35], v[34:35], v[38:39]
	v_ashrrev_i32_e32 v77, 31, v76
	s_waitcnt lgkmcnt(0)
	v_mfma_f32_16x16x32_bf16 v[46:49], v[86:89], v[90:93], v[46:49]
	s_nop 7
	v_pk_add_f32 v[38:39], v[42:43], v[46:47]
	s_nop 0
	v_pk_add_f32 v[38:39], v[34:35], v[38:39]
	v_lshlrev_b64 v[34:35], 13, v[76:77]
	v_lshl_add_u64 v[34:35], s[24:25], 0, v[34:35]
	v_mov_b32_dpp v42, v38 quad_perm:[1,0,3,2] row_mask:0xf bank_mask:0xf bound_ctrl:1
	v_max_f32_e32 v42, v42, v42
	v_max_f32_e32 v42, v38, v42
	s_nop 1
	v_mov_b32_dpp v43, v42 quad_perm:[2,3,0,1] row_mask:0xf bank_mask:0xf bound_ctrl:1
	v_max_f32_e32 v43, v43, v43
	v_max_f32_e32 v42, v42, v43
	s_nop 1
	v_mov_b32_dpp v43, v42 row_half_mirror row_mask:0xf bank_mask:0xf bound_ctrl:1
	v_max_f32_e32 v43, v43, v43
	v_max_f32_e32 v42, v42, v43
	s_nop 1
	v_mov_b32_dpp v43, v42 row_mirror row_mask:0xf bank_mask:0xf bound_ctrl:1
	v_max_f32_e32 v43, v43, v43
	v_max_f32_e32 v42, v42, v43
	v_sub_f32_e32 v38, v38, v42
	v_mul_f32_e32 v38, 0x3fb8aa3b, v38
	v_exp_f32_e32 v38, v38
	s_nop 1
	v_add_f32_dpp v42, v38, v38 quad_perm:[1,0,3,2] row_mask:0xf bank_mask:0xf bound_ctrl:1
	s_nop 1
	v_add_f32_dpp v42, v42, v42 quad_perm:[2,3,0,1] row_mask:0xf bank_mask:0xf bound_ctrl:1
	s_nop 1
	v_add_f32_dpp v42, v42, v42 row_half_mirror row_mask:0xf bank_mask:0xf bound_ctrl:1
	s_nop 1
	v_mov_b32_dpp v43, v42 row_mirror row_mask:0xf bank_mask:0xf bound_ctrl:1
	s_and_saveexec_b64 s[26:27], vcc
	s_cbranch_execz .LBB0_2522
	v_add_f32_e32 v42, v42, v43
	v_rcp_f32_e32 v42, v42
	s_sub_i32 s19, s18, 24
	s_ashr_i32 s0, s19, 11
	s_ashr_i32 s1, s0, 31
	s_and_b32 s19, s19, 0x7ff
	s_lshl_b64 s[0:1], s[0:1], 17
	v_mul_f32_e32 v38, v38, v42
	v_lshl_add_u64 v[42:43], v[34:35], 0, s[0:1]
	s_lshl_b32 s22, s19, 2
	v_lshl_add_u64 v[42:43], v[42:43], 0, s[22:23]
	global_store_dword v[42:43], v38, off
